# v14: G2s epilogue - main-pass loads (20) issued before waiting on the 4 row-statistic loads (one round trip instead of two), on top of v10
# speedup vs baseline: 1.0022x; 1.0022x over previous
.LBB0_510:
	s_or_b64 exec, exec, s[6:7]
	s_movk_i32 s0, 0x100
	v_cmp_gt_i32_e32 vcc, s0, v95
	s_lshl_b32 s6, s84, 8
	s_barrier
	v_mov_b32_e32 v223, v95
	s_and_saveexec_b64 s[0:1], vcc
	s_cbranch_execz .Lg2s0_a
	v_add_u32_e32 v238, s6, v95
	v_ashrrev_i32_e32 v239, 31, v238
	v_lshl_add_u64 v[238:239], v[238:239], 4, s[8:9]
	global_load_dword v240, v[238:239], off sc1
	global_load_dword v241, v[238:239], off offset:4 sc1
	global_load_dword v242, v[238:239], off offset:8 sc1
	s_nop 0
	global_load_dword v238, v[238:239], off offset:12 sc1
.Lg2s0_a:
	s_or_b64 exec, exec, s[0:1]
	s_add_u32 s4, s24, 0x6036000
	v_readlane_b32 s0, v255, 21
	s_addc_u32 s5, s25, 0
	s_or_b32 s0, s27, s0
	v_lshl_add_u32 v94, v94, 3, s0
	v_add_u32_e32 v0, s26, v114
	v_ashrrev_i32_e32 v95, 31, v94
	v_add_u32_e32 v102, s6, v0
	v_lshlrev_b64 v[202:203], 1, v[94:95]
	v_ashrrev_i32_e32 v103, 31, v102
	v_lshl_add_u64 v[114:115], s[4:5], 0, v[202:203]
	v_lshlrev_b64 v[218:219], 11, v[102:103]
	v_lshl_add_u64 v[116:117], v[114:115], 0, v[218:219]
	global_load_dwordx4 v[198:201], v[116:117], off
	v_mov_b32_e32 v96, s22
	v_mov_b32_e32 v97, s23
	v_lshl_add_u64 v[118:119], v[94:95], 2, v[96:97]
	global_load_dwordx4 v[110:113], v[118:119], off
	global_load_dwordx4 v[94:97], v[118:119], off offset:16
	v_mul_f32_e32 v104, 0xbfb8aa3b, v160
	v_mul_f32_e32 v103, 0xbfb8aa3b, v159
	v_mul_f32_e32 v105, 0xbfb8aa3b, v161
	v_lshl_add_u32 v0, v0, 2, 0
	v_exp_f32_e32 v151, v104
	v_add_u32_e32 v104, 16, v102
	v_add_u32_e32 v120, 32, v102
	v_add_u32_e32 v126, 48, v102
	v_add_u32_e32 v128, 0x80, v102
	v_add_u32_e32 v142, 0x90, v102
	v_add_u32_e32 v144, 0xa0, v102
	v_add_u32_e32 v102, 0xb0, v102
	v_exp_f32_e32 v150, v103
	v_exp_f32_e32 v152, v105
	v_add_u32_e32 v222, 0x21000, v0
	v_ashrrev_i32_e32 v105, 31, v104
	v_ashrrev_i32_e32 v121, 31, v120
	v_ashrrev_i32_e32 v103, 31, v102
	s_nop 0
	v_lshlrev_b64 v[216:217], 11, v[104:105]
	v_lshlrev_b64 v[214:215], 11, v[120:121]
	v_lshlrev_b64 v[204:205], 11, v[102:103]
	global_load_dwordx4 v[102:105], v[118:119], off offset:528
	s_nop 0
	global_load_dwordx4 v[118:121], v[118:119], off offset:512
	s_nop 0
	global_load_dwordx4 v[224:227], v[116:117], off offset:256
	v_mul_f32_e32 v1, 0xbfb8aa3b, v158
	v_exp_f32_e32 v1, v1
	v_ashrrev_i32_e32 v127, 31, v126
	v_ashrrev_i32_e32 v129, 31, v128
	v_ashrrev_i32_e32 v143, 31, v142
	v_ashrrev_i32_e32 v145, 31, v144
	v_lshlrev_b64 v[212:213], 11, v[126:127]
	v_lshlrev_b64 v[210:211], 11, v[128:129]
	v_lshlrev_b64 v[208:209], 11, v[142:143]
	v_lshlrev_b64 v[206:207], 11, v[144:145]
	v_add_f32_e32 v0, 1.0, v1
	v_add_f32_e32 v1, 1.0, v150
	v_add_f32_e32 v150, 1.0, v151
	v_add_f32_e32 v151, 1.0, v152
	v_lshl_add_u64 v[116:117], v[114:115], 0, v[216:217]
	v_lshl_add_u64 v[126:127], v[114:115], 0, v[214:215]
	v_lshl_add_u64 v[128:129], v[114:115], 0, v[212:213]
	v_lshl_add_u64 v[142:143], v[114:115], 0, v[210:211]
	v_lshl_add_u64 v[144:145], v[114:115], 0, v[208:209]
	v_lshl_add_u64 v[232:233], v[114:115], 0, v[206:207]
	v_lshl_add_u64 v[114:115], v[114:115], 0, v[204:205]
	v_rcp_f32_e32 v236, v150
	v_rcp_f32_e32 v237, v151
	global_load_dwordx4 v[228:231], v[116:117], off
	global_load_dwordx4 v[194:197], v[116:117], off offset:256
	global_load_dwordx4 v[190:193], v[126:127], off
	global_load_dwordx4 v[186:189], v[126:127], off offset:256
	global_load_dwordx4 v[182:185], v[128:129], off
	global_load_dwordx4 v[178:181], v[128:129], off offset:256
	global_load_dwordx4 v[174:177], v[142:143], off
	global_load_dwordx4 v[170:173], v[142:143], off offset:256
	global_load_dwordx4 v[166:169], v[144:145], off
	global_load_dwordx4 v[162:165], v[144:145], off offset:256
	global_load_dwordx4 v[150:153], v[232:233], off
	s_nop 0
	global_load_dwordx4 v[142:145], v[232:233], off offset:256
	global_load_dwordx4 v[126:129], v[114:115], off
	s_nop 0
	global_load_dwordx4 v[114:117], v[114:115], off offset:256
	v_rcp_f32_e32 v234, v0
	v_mul_f32_e32 v0, 0xbfb8aa3b, v154
	v_rcp_f32_e32 v235, v1
	v_exp_f32_e32 v0, v0
	v_mul_f32_e32 v1, 0xbfb8aa3b, v155
	v_exp_f32_e32 v1, v1
	v_pk_mul_f32 v[160:161], v[160:161], v[236:237]
	v_add_f32_e32 v0, 1.0, v0
	v_pk_mul_f32 v[158:159], v[158:159], v[234:235]
	s_cmpk_lt_i32 s92, 0x300
	s_mul_hi_i32 s0, s64, 0x2aaaaaab
	s_cselect_b64 s[16:17], -1, 0
	s_lshr_b32 s1, s0, 31
	s_ashr_i32 s0, s0, 4
	s_add_i32 s0, s0, s1
	s_lshl_b32 s1, s0, 3
	s_mulk_i32 s0, 0x60
	s_sub_i32 s0, s64, s0
	s_bfe_i32 s2, s0, 0x80000
	s_bfe_u32 s2, s2, 0x3000c
	s_add_i32 s2, s0, s2
	v_writelane_b32 v255, s6, 22
	s_mov_b32 s14, 0x1ffff0
	s_mov_b32 s15, 0x7fffe0
	s_movk_i32 s100, 0x100
	v_cmp_gt_i32_e32 vcc, s100, v223
	s_and_saveexec_b64 s[98:99], vcc
	s_cbranch_execz .Lg2s0_b
	v_mov_b32_e32 v239, 0x358637bd
	s_mov_b32 s100, 0x800000
	s_waitcnt vmcnt(20)
	v_add_f32_e32 v240, v241, v240
	v_add_f32_e32 v240, v240, v242
	v_add_f32_e32 v240, v240, v238
	v_fmac_f32_e32 v239, 0x3a800000, v240
	v_mul_f32_e32 v240, 0x4b800000, v239
	v_cmp_gt_f32_e32 vcc, s100, v239
	v_lshl_add_u32 v241, v223, 2, 0
	v_add_u32_e32 v241, 0x21000, v241
	v_cndmask_b32_e32 v240, v239, v240, vcc
	v_rsq_f32_e32 v240, v240
	s_nop 0
	v_mul_f32_e32 v243, 0x45800000, v240
	v_cndmask_b32_e32 v240, v240, v243, vcc
	ds_write_b32 v241, v240
.Lg2s0_b:
	s_or_b64 exec, exec, s[98:99]
	s_waitcnt lgkmcnt(0)
	s_barrier
	ds_read2_b32 v[220:221], v222 offset1:16
	s_waitcnt vmcnt(0)
	v_lshlrev_b32_e32 v232, 16, v198
	v_and_b32_e32 v233, 0xffff0000, v198
	v_lshlrev_b32_e32 v198, 16, v199
	v_and_b32_e32 v199, 0xffff0000, v199
	s_waitcnt lgkmcnt(0)
	v_pk_mul_f32 v[198:199], v[220:221], v[198:199] op_sel_hi:[0,1]
	v_pk_mul_f32 v[198:199], v[112:113], v[198:199]
	v_pk_mul_f32 v[232:233], v[220:221], v[232:233] op_sel_hi:[0,1]
	v_pk_mul_f32 v[160:161], v[160:161], v[198:199]
	v_rcp_f32_e32 v198, v0
	v_add_f32_e32 v0, 1.0, v1
	v_rcp_f32_e32 v199, v0
	v_mul_f32_e32 v0, 0xbfb8aa3b, v156
	v_exp_f32_e32 v0, v0
	v_mul_f32_e32 v1, 0xbfb8aa3b, v157
	v_pk_mul_f32 v[232:233], v[110:111], v[232:233]
	v_exp_f32_e32 v1, v1
	v_pk_mul_f32 v[158:159], v[158:159], v[232:233]
	v_lshlrev_b32_e32 v232, 16, v200
	v_and_b32_e32 v233, 0xffff0000, v200
	v_pk_mul_f32 v[232:233], v[220:221], v[232:233] op_sel_hi:[0,1]
	v_pk_mul_f32 v[232:233], v[94:95], v[232:233]
	v_pk_mul_f32 v[154:155], v[154:155], v[198:199]
	v_add_f32_e32 v0, 1.0, v0
	v_pk_mul_f32 v[198:199], v[154:155], v[232:233]
	v_rcp_f32_e32 v154, v0
	v_add_f32_e32 v0, 1.0, v1
	v_rcp_f32_e32 v155, v0
	v_mul_f32_e32 v0, 0xbfb8aa3b, v146
	v_exp_f32_e32 v0, v0
	v_mul_f32_e32 v1, 0xbfb8aa3b, v147
	v_exp_f32_e32 v1, v1
	v_lshlrev_b32_e32 v200, 16, v201
	v_and_b32_e32 v201, 0xffff0000, v201
	v_pk_mul_f32 v[200:201], v[220:221], v[200:201] op_sel_hi:[0,1]
	v_pk_mul_f32 v[200:201], v[96:97], v[200:201]
	v_pk_mul_f32 v[154:155], v[156:157], v[154:155]
	v_add_f32_e32 v0, 1.0, v0
	v_pk_mul_f32 v[200:201], v[154:155], v[200:201]
	v_cvt_pk_bf16_f32 v155, v160, v161
	v_rcp_f32_e32 v160, v0
	v_add_f32_e32 v0, 1.0, v1
	v_rcp_f32_e32 v161, v0
	v_mul_f32_e32 v0, 0xbfb8aa3b, v148
	v_exp_f32_e32 v0, v0
	v_mul_f32_e32 v1, 0xbfb8aa3b, v149
	v_exp_f32_e32 v1, v1
	v_pk_mul_f32 v[146:147], v[146:147], v[160:161]
	v_add_f32_e32 v0, 1.0, v0
	v_rcp_f32_e32 v160, v0
	v_add_f32_e32 v0, 1.0, v1
	v_rcp_f32_e32 v161, v0
	v_mul_f32_e32 v0, 0xbfb8aa3b, v138
	v_exp_f32_e32 v0, v0
	v_mul_f32_e32 v1, 0xbfb8aa3b, v139
	v_exp_f32_e32 v1, v1
	v_cvt_pk_bf16_f32 v156, v198, v199
	v_lshlrev_b32_e32 v198, 16, v224
	v_and_b32_e32 v199, 0xffff0000, v224
	v_pk_mul_f32 v[198:199], v[220:221], v[198:199] op_sel_hi:[0,1]
	v_add_f32_e32 v0, 1.0, v0
	v_pk_mul_f32 v[198:199], v[118:119], v[198:199]
	v_pk_mul_f32 v[148:149], v[148:149], v[160:161]
	v_rcp_f32_e32 v160, v0
	v_add_f32_e32 v0, 1.0, v1
	v_pk_mul_f32 v[146:147], v[146:147], v[198:199]
	v_lshlrev_b32_e32 v198, 16, v225
	v_and_b32_e32 v199, 0xffff0000, v225
	v_rcp_f32_e32 v161, v0
	v_mul_f32_e32 v0, 0xbfb8aa3b, v140
	v_pk_mul_f32 v[198:199], v[220:221], v[198:199] op_sel_hi:[0,1]
	v_exp_f32_e32 v0, v0
	v_mul_f32_e32 v1, 0xbfb8aa3b, v141
	v_pk_mul_f32 v[198:199], v[120:121], v[198:199]
	v_exp_f32_e32 v1, v1
	v_pk_mul_f32 v[148:149], v[148:149], v[198:199]
	v_lshlrev_b32_e32 v198, 16, v226
	v_and_b32_e32 v199, 0xffff0000, v226
	v_pk_mul_f32 v[198:199], v[220:221], v[198:199] op_sel_hi:[0,1]
	v_pk_mul_f32 v[198:199], v[102:103], v[198:199]
	v_pk_mul_f32 v[138:139], v[138:139], v[160:161]
	v_add_f32_e32 v0, 1.0, v0
	v_pk_mul_f32 v[160:161], v[138:139], v[198:199]
	v_rcp_f32_e32 v138, v0
	v_add_f32_e32 v0, 1.0, v1
	v_cvt_pk_bf16_f32 v154, v158, v159
	v_lshl_add_u64 v[158:159], s[4:5], 0, v[218:219]
	v_rcp_f32_e32 v139, v0
	v_cvt_pk_bf16_f32 v157, v200, v201
	v_lshl_add_u64 v[158:159], v[158:159], 0, v[202:203]
	v_mul_f32_e32 v0, 0xbfb8aa3b, v134
	global_store_dwordx4 v[158:159], v[154:157], off
	v_exp_f32_e32 v0, v0
	v_mul_f32_e32 v1, 0xbfb8aa3b, v135
	v_lshlrev_b32_e32 v154, 16, v227
	v_and_b32_e32 v155, 0xffff0000, v227
	v_pk_mul_f32 v[154:155], v[220:221], v[154:155] op_sel_hi:[0,1]
	v_exp_f32_e32 v1, v1
	v_pk_mul_f32 v[154:155], v[104:105], v[154:155]
	v_pk_mul_f32 v[138:139], v[140:141], v[138:139]
	v_cvt_pk_bf16_f32 v140, v160, v161
	v_pk_mul_f32 v[154:155], v[138:139], v[154:155]
	v_cvt_pk_bf16_f32 v138, v146, v147
	v_cvt_pk_bf16_f32 v139, v148, v149
	v_cvt_pk_bf16_f32 v141, v154, v155
	v_add_f32_e32 v0, 1.0, v0
	global_store_dwordx4 v[158:159], v[138:141], off offset:256
	v_mov_b32_e32 v146, v221
	s_nop 0
	v_rcp_f32_e32 v138, v0
	v_add_f32_e32 v0, 1.0, v1
	v_rcp_f32_e32 v139, v0
	v_mul_f32_e32 v0, 0xbfb8aa3b, v136
	v_exp_f32_e32 v0, v0
	v_mul_f32_e32 v1, 0xbfb8aa3b, v137
	v_exp_f32_e32 v1, v1
	v_pk_mul_f32 v[134:135], v[134:135], v[138:139]
	v_add_f32_e32 v0, 1.0, v0
	v_rcp_f32_e32 v138, v0
	v_add_f32_e32 v0, 1.0, v1
	v_rcp_f32_e32 v139, v0
	v_mul_f32_e32 v0, 0xbfb8aa3b, v130
	v_exp_f32_e32 v0, v0
	v_mul_f32_e32 v1, 0xbfb8aa3b, v131
	v_exp_f32_e32 v1, v1
	v_lshlrev_b32_e32 v140, 16, v228
	v_and_b32_e32 v141, 0xffff0000, v228
	v_pk_mul_f32 v[140:141], v[146:147], v[140:141] op_sel_hi:[0,1]
	v_add_f32_e32 v0, 1.0, v0
	v_pk_mul_f32 v[140:141], v[110:111], v[140:141]
	v_pk_mul_f32 v[136:137], v[136:137], v[138:139]
	v_rcp_f32_e32 v138, v0
	v_add_f32_e32 v0, 1.0, v1
	v_pk_mul_f32 v[134:135], v[134:135], v[140:141]
	v_lshlrev_b32_e32 v140, 16, v229
	v_and_b32_e32 v141, 0xffff0000, v229
	v_rcp_f32_e32 v139, v0
	v_mul_f32_e32 v0, 0xbfb8aa3b, v132
	v_pk_mul_f32 v[140:141], v[146:147], v[140:141] op_sel_hi:[0,1]
	v_exp_f32_e32 v0, v0
	v_mul_f32_e32 v1, 0xbfb8aa3b, v133
	v_pk_mul_f32 v[140:141], v[112:113], v[140:141]
	v_exp_f32_e32 v1, v1
	v_pk_mul_f32 v[136:137], v[136:137], v[140:141]
	v_lshlrev_b32_e32 v140, 16, v230
	v_and_b32_e32 v141, 0xffff0000, v230
	v_pk_mul_f32 v[140:141], v[146:147], v[140:141] op_sel_hi:[0,1]
	v_pk_mul_f32 v[140:141], v[94:95], v[140:141]
	v_pk_mul_f32 v[130:131], v[130:131], v[138:139]
	v_add_f32_e32 v0, 1.0, v0
	v_pk_mul_f32 v[138:139], v[130:131], v[140:141]
	v_rcp_f32_e32 v130, v0
	v_add_f32_e32 v0, 1.0, v1
	v_rcp_f32_e32 v131, v0
	v_mul_f32_e32 v0, 0xbfb8aa3b, v122
	v_lshlrev_b32_e32 v140, 16, v231
	v_and_b32_e32 v141, 0xffff0000, v231
	v_exp_f32_e32 v0, v0
	v_mul_f32_e32 v1, 0xbfb8aa3b, v123
	v_pk_mul_f32 v[140:141], v[146:147], v[140:141] op_sel_hi:[0,1]
	v_exp_f32_e32 v1, v1
	v_pk_mul_f32 v[140:141], v[96:97], v[140:141]
	v_pk_mul_f32 v[130:131], v[132:133], v[130:131]
	v_cvt_pk_bf16_f32 v132, v138, v139
	v_pk_mul_f32 v[140:141], v[130:131], v[140:141]
	v_cvt_pk_bf16_f32 v130, v134, v135
	v_lshl_add_u64 v[134:135], s[4:5], 0, v[216:217]
	v_cvt_pk_bf16_f32 v131, v136, v137
	v_cvt_pk_bf16_f32 v133, v140, v141
	v_lshl_add_u64 v[134:135], v[134:135], 0, v[202:203]
	v_add_f32_e32 v0, 1.0, v0
	global_store_dwordx4 v[134:135], v[130:133], off
	s_nop 1
	v_rcp_f32_e32 v130, v0
	v_add_f32_e32 v0, 1.0, v1
	v_rcp_f32_e32 v131, v0
	v_mul_f32_e32 v0, 0xbfb8aa3b, v124
	v_exp_f32_e32 v0, v0
	v_mul_f32_e32 v1, 0xbfb8aa3b, v125
	v_exp_f32_e32 v1, v1
	v_pk_mul_f32 v[122:123], v[122:123], v[130:131]
	v_add_f32_e32 v0, 1.0, v0
	v_rcp_f32_e32 v130, v0
	v_add_f32_e32 v0, 1.0, v1
	v_rcp_f32_e32 v131, v0
	v_mul_f32_e32 v0, 0xbfb8aa3b, v106
	v_exp_f32_e32 v0, v0
	v_mul_f32_e32 v1, 0xbfb8aa3b, v107
	v_exp_f32_e32 v1, v1
	v_lshlrev_b32_e32 v132, 16, v194
	v_and_b32_e32 v133, 0xffff0000, v194
	v_pk_mul_f32 v[132:133], v[146:147], v[132:133] op_sel_hi:[0,1]
	v_add_f32_e32 v0, 1.0, v0
	v_pk_mul_f32 v[132:133], v[118:119], v[132:133]
	v_pk_mul_f32 v[124:125], v[124:125], v[130:131]
	v_rcp_f32_e32 v130, v0
	v_add_f32_e32 v0, 1.0, v1
	v_pk_mul_f32 v[122:123], v[122:123], v[132:133]
	v_lshlrev_b32_e32 v132, 16, v195
	v_and_b32_e32 v133, 0xffff0000, v195
	v_rcp_f32_e32 v131, v0
	v_mul_f32_e32 v0, 0xbfb8aa3b, v108
	v_pk_mul_f32 v[132:133], v[146:147], v[132:133] op_sel_hi:[0,1]
	v_exp_f32_e32 v0, v0
	v_mul_f32_e32 v1, 0xbfb8aa3b, v109
	v_pk_mul_f32 v[132:133], v[120:121], v[132:133]
	v_exp_f32_e32 v1, v1
	v_pk_mul_f32 v[124:125], v[124:125], v[132:133]
	v_lshlrev_b32_e32 v132, 16, v196
	v_and_b32_e32 v133, 0xffff0000, v196
	v_pk_mul_f32 v[132:133], v[146:147], v[132:133] op_sel_hi:[0,1]
	v_pk_mul_f32 v[132:133], v[102:103], v[132:133]
	v_pk_mul_f32 v[106:107], v[106:107], v[130:131]
	v_add_f32_e32 v0, 1.0, v0
	v_pk_mul_f32 v[130:131], v[106:107], v[132:133]
	v_rcp_f32_e32 v106, v0
	v_add_f32_e32 v0, 1.0, v1
	v_rcp_f32_e32 v107, v0
	v_mul_f32_e32 v0, 0xbfb8aa3b, v98
	v_lshlrev_b32_e32 v132, 16, v197
	v_and_b32_e32 v133, 0xffff0000, v197
	v_exp_f32_e32 v0, v0
	v_mul_f32_e32 v1, 0xbfb8aa3b, v99
	v_pk_mul_f32 v[132:133], v[146:147], v[132:133] op_sel_hi:[0,1]
	v_exp_f32_e32 v1, v1
	v_pk_mul_f32 v[132:133], v[104:105], v[132:133]
	v_pk_mul_f32 v[106:107], v[108:109], v[106:107]
	v_cvt_pk_bf16_f32 v108, v130, v131
	v_pk_mul_f32 v[132:133], v[106:107], v[132:133]
	v_cvt_pk_bf16_f32 v106, v122, v123
	v_cvt_pk_bf16_f32 v107, v124, v125
	v_cvt_pk_bf16_f32 v109, v132, v133
	v_add_f32_e32 v0, 1.0, v0
	global_store_dwordx4 v[134:135], v[106:109], off offset:256
	ds_read2_b32 v[106:107], v222 offset0:32 offset1:48
	v_lshlrev_b32_e32 v122, 16, v190
	v_rcp_f32_e32 v108, v0
	v_add_f32_e32 v0, 1.0, v1
	v_rcp_f32_e32 v109, v0
	v_mul_f32_e32 v0, 0xbfb8aa3b, v100
	v_exp_f32_e32 v0, v0
	v_mul_f32_e32 v1, 0xbfb8aa3b, v101
	v_exp_f32_e32 v1, v1
	v_pk_mul_f32 v[98:99], v[98:99], v[108:109]
	v_add_f32_e32 v0, 1.0, v0
	v_rcp_f32_e32 v108, v0
	v_add_f32_e32 v0, 1.0, v1
	v_rcp_f32_e32 v109, v0
	v_mul_f32_e32 v0, 0xbfb8aa3b, v90
	v_exp_f32_e32 v0, v0
	v_mul_f32_e32 v1, 0xbfb8aa3b, v91
	v_exp_f32_e32 v1, v1
	v_and_b32_e32 v123, 0xffff0000, v190
	s_waitcnt lgkmcnt(0)
	v_pk_mul_f32 v[122:123], v[106:107], v[122:123] op_sel_hi:[0,1]
	v_add_f32_e32 v0, 1.0, v0
	v_pk_mul_f32 v[122:123], v[110:111], v[122:123]
	v_pk_mul_f32 v[100:101], v[100:101], v[108:109]
	v_rcp_f32_e32 v108, v0
	v_add_f32_e32 v0, 1.0, v1
	v_pk_mul_f32 v[98:99], v[98:99], v[122:123]
	v_lshlrev_b32_e32 v122, 16, v191
	v_and_b32_e32 v123, 0xffff0000, v191
	v_rcp_f32_e32 v109, v0
	v_mul_f32_e32 v0, 0xbfb8aa3b, v92
	v_pk_mul_f32 v[122:123], v[106:107], v[122:123] op_sel_hi:[0,1]
	v_exp_f32_e32 v0, v0
	v_mul_f32_e32 v1, 0xbfb8aa3b, v93
	v_pk_mul_f32 v[122:123], v[112:113], v[122:123]
	v_exp_f32_e32 v1, v1
	v_pk_mul_f32 v[100:101], v[100:101], v[122:123]
	v_lshlrev_b32_e32 v122, 16, v192
	v_and_b32_e32 v123, 0xffff0000, v192
	v_pk_mul_f32 v[122:123], v[106:107], v[122:123] op_sel_hi:[0,1]
	v_pk_mul_f32 v[122:123], v[94:95], v[122:123]
	v_pk_mul_f32 v[90:91], v[90:91], v[108:109]
	v_add_f32_e32 v0, 1.0, v0
	v_pk_mul_f32 v[108:109], v[90:91], v[122:123]
	v_rcp_f32_e32 v90, v0
	v_add_f32_e32 v0, 1.0, v1
	v_rcp_f32_e32 v91, v0
	v_mul_f32_e32 v0, 0xbfb8aa3b, v86
	v_lshlrev_b32_e32 v122, 16, v193
	v_and_b32_e32 v123, 0xffff0000, v193
	v_exp_f32_e32 v0, v0
	v_mul_f32_e32 v1, 0xbfb8aa3b, v87
	v_pk_mul_f32 v[122:123], v[106:107], v[122:123] op_sel_hi:[0,1]
	v_exp_f32_e32 v1, v1
	v_pk_mul_f32 v[122:123], v[96:97], v[122:123]
	v_pk_mul_f32 v[90:91], v[92:93], v[90:91]
	v_cvt_pk_bf16_f32 v92, v108, v109
	v_pk_mul_f32 v[122:123], v[90:91], v[122:123]
	v_cvt_pk_bf16_f32 v90, v98, v99
	v_lshl_add_u64 v[98:99], s[4:5], 0, v[214:215]
	v_cvt_pk_bf16_f32 v91, v100, v101
	v_cvt_pk_bf16_f32 v93, v122, v123
	v_lshl_add_u64 v[98:99], v[98:99], 0, v[202:203]
	v_add_f32_e32 v0, 1.0, v0
	global_store_dwordx4 v[98:99], v[90:93], off
	s_nop 1
	v_rcp_f32_e32 v90, v0
	v_add_f32_e32 v0, 1.0, v1
	v_rcp_f32_e32 v91, v0
	v_mul_f32_e32 v0, 0xbfb8aa3b, v88
	v_exp_f32_e32 v0, v0
	v_mul_f32_e32 v1, 0xbfb8aa3b, v89
	v_exp_f32_e32 v1, v1
	v_pk_mul_f32 v[86:87], v[86:87], v[90:91]
	v_add_f32_e32 v0, 1.0, v0
	v_rcp_f32_e32 v90, v0
	v_add_f32_e32 v0, 1.0, v1
	v_rcp_f32_e32 v91, v0
	v_mul_f32_e32 v0, 0xbfb8aa3b, v82
	v_exp_f32_e32 v0, v0
	v_mul_f32_e32 v1, 0xbfb8aa3b, v83
	v_exp_f32_e32 v1, v1
	v_lshlrev_b32_e32 v92, 16, v186
	v_and_b32_e32 v93, 0xffff0000, v186
	v_pk_mul_f32 v[92:93], v[106:107], v[92:93] op_sel_hi:[0,1]
	v_add_f32_e32 v0, 1.0, v0
	v_pk_mul_f32 v[92:93], v[118:119], v[92:93]
	v_pk_mul_f32 v[88:89], v[88:89], v[90:91]
	v_rcp_f32_e32 v90, v0
	v_add_f32_e32 v0, 1.0, v1
	v_pk_mul_f32 v[86:87], v[86:87], v[92:93]
	v_lshlrev_b32_e32 v92, 16, v187
	v_and_b32_e32 v93, 0xffff0000, v187
	v_rcp_f32_e32 v91, v0
	v_mul_f32_e32 v0, 0xbfb8aa3b, v84
	v_pk_mul_f32 v[92:93], v[106:107], v[92:93] op_sel_hi:[0,1]
	v_exp_f32_e32 v0, v0
	v_mul_f32_e32 v1, 0xbfb8aa3b, v85
	v_pk_mul_f32 v[92:93], v[120:121], v[92:93]
	v_exp_f32_e32 v1, v1
	v_pk_mul_f32 v[88:89], v[88:89], v[92:93]
	v_lshlrev_b32_e32 v92, 16, v188
	v_and_b32_e32 v93, 0xffff0000, v188
	v_pk_mul_f32 v[92:93], v[106:107], v[92:93] op_sel_hi:[0,1]
	v_pk_mul_f32 v[92:93], v[102:103], v[92:93]
	v_pk_mul_f32 v[82:83], v[82:83], v[90:91]
	v_add_f32_e32 v0, 1.0, v0
	v_pk_mul_f32 v[90:91], v[82:83], v[92:93]
	v_rcp_f32_e32 v82, v0
	v_add_f32_e32 v0, 1.0, v1
	v_rcp_f32_e32 v83, v0
	v_mul_f32_e32 v0, 0xbfb8aa3b, v78
	v_lshlrev_b32_e32 v92, 16, v189
	v_and_b32_e32 v93, 0xffff0000, v189
	v_exp_f32_e32 v0, v0
	v_mul_f32_e32 v1, 0xbfb8aa3b, v79
	v_pk_mul_f32 v[92:93], v[106:107], v[92:93] op_sel_hi:[0,1]
	v_exp_f32_e32 v1, v1
	v_pk_mul_f32 v[92:93], v[104:105], v[92:93]
	v_pk_mul_f32 v[82:83], v[84:85], v[82:83]
	v_cvt_pk_bf16_f32 v84, v90, v91
	v_pk_mul_f32 v[92:93], v[82:83], v[92:93]
	v_cvt_pk_bf16_f32 v82, v86, v87
	v_cvt_pk_bf16_f32 v83, v88, v89
	v_cvt_pk_bf16_f32 v85, v92, v93
	v_add_f32_e32 v0, 1.0, v0
	global_store_dwordx4 v[98:99], v[82:85], off offset:256
	v_mov_b32_e32 v86, v107
	s_nop 0
	v_rcp_f32_e32 v82, v0
	v_add_f32_e32 v0, 1.0, v1
	v_rcp_f32_e32 v83, v0
	v_mul_f32_e32 v0, 0xbfb8aa3b, v80
	v_exp_f32_e32 v0, v0
	v_mul_f32_e32 v1, 0xbfb8aa3b, v81
	v_exp_f32_e32 v1, v1
	v_pk_mul_f32 v[78:79], v[78:79], v[82:83]
	v_add_f32_e32 v0, 1.0, v0
	v_rcp_f32_e32 v82, v0
	v_add_f32_e32 v0, 1.0, v1
	v_rcp_f32_e32 v83, v0
	v_mul_f32_e32 v0, 0xbfb8aa3b, v74
	v_exp_f32_e32 v0, v0
	v_mul_f32_e32 v1, 0xbfb8aa3b, v75
	v_exp_f32_e32 v1, v1
	v_lshlrev_b32_e32 v84, 16, v182
	v_and_b32_e32 v85, 0xffff0000, v182
	v_pk_mul_f32 v[84:85], v[86:87], v[84:85] op_sel_hi:[0,1]
	v_add_f32_e32 v0, 1.0, v0
	v_pk_mul_f32 v[84:85], v[110:111], v[84:85]
	v_pk_mul_f32 v[80:81], v[80:81], v[82:83]
	v_rcp_f32_e32 v82, v0
	v_add_f32_e32 v0, 1.0, v1
	v_pk_mul_f32 v[78:79], v[78:79], v[84:85]
	v_lshlrev_b32_e32 v84, 16, v183
	v_and_b32_e32 v85, 0xffff0000, v183
	v_rcp_f32_e32 v83, v0
	v_mul_f32_e32 v0, 0xbfb8aa3b, v76
	v_pk_mul_f32 v[84:85], v[86:87], v[84:85] op_sel_hi:[0,1]
	v_exp_f32_e32 v0, v0
	v_mul_f32_e32 v1, 0xbfb8aa3b, v77
	v_pk_mul_f32 v[84:85], v[112:113], v[84:85]
	v_exp_f32_e32 v1, v1
	v_pk_mul_f32 v[80:81], v[80:81], v[84:85]
	v_lshlrev_b32_e32 v84, 16, v184
	v_and_b32_e32 v85, 0xffff0000, v184
	v_pk_mul_f32 v[84:85], v[86:87], v[84:85] op_sel_hi:[0,1]
	v_pk_mul_f32 v[84:85], v[94:95], v[84:85]
	v_pk_mul_f32 v[74:75], v[74:75], v[82:83]
	v_add_f32_e32 v0, 1.0, v0
	v_pk_mul_f32 v[82:83], v[74:75], v[84:85]
	v_rcp_f32_e32 v74, v0
	v_add_f32_e32 v0, 1.0, v1
	v_rcp_f32_e32 v75, v0
	v_mul_f32_e32 v0, 0xbfb8aa3b, v70
	v_lshlrev_b32_e32 v84, 16, v185
	v_and_b32_e32 v85, 0xffff0000, v185
	v_exp_f32_e32 v0, v0
	v_mul_f32_e32 v1, 0xbfb8aa3b, v71
	v_pk_mul_f32 v[84:85], v[86:87], v[84:85] op_sel_hi:[0,1]
	v_exp_f32_e32 v1, v1
	v_pk_mul_f32 v[84:85], v[96:97], v[84:85]
	v_pk_mul_f32 v[74:75], v[76:77], v[74:75]
	v_cvt_pk_bf16_f32 v76, v82, v83
	v_pk_mul_f32 v[84:85], v[74:75], v[84:85]
	v_cvt_pk_bf16_f32 v74, v78, v79
	v_lshl_add_u64 v[78:79], s[4:5], 0, v[212:213]
	v_cvt_pk_bf16_f32 v75, v80, v81
	v_cvt_pk_bf16_f32 v77, v84, v85
	v_lshl_add_u64 v[78:79], v[78:79], 0, v[202:203]
	v_add_f32_e32 v0, 1.0, v0
	global_store_dwordx4 v[78:79], v[74:77], off
	s_nop 1
	v_rcp_f32_e32 v74, v0
	v_add_f32_e32 v0, 1.0, v1
	v_rcp_f32_e32 v75, v0
	v_mul_f32_e32 v0, 0xbfb8aa3b, v72
	v_exp_f32_e32 v0, v0
	v_mul_f32_e32 v1, 0xbfb8aa3b, v73
	v_exp_f32_e32 v1, v1
	v_pk_mul_f32 v[70:71], v[70:71], v[74:75]
	v_add_f32_e32 v0, 1.0, v0
	v_rcp_f32_e32 v74, v0
	v_add_f32_e32 v0, 1.0, v1
	v_rcp_f32_e32 v75, v0
	v_mul_f32_e32 v0, 0xbfb8aa3b, v66
	v_exp_f32_e32 v0, v0
	v_mul_f32_e32 v1, 0xbfb8aa3b, v67
	v_exp_f32_e32 v1, v1
	v_lshlrev_b32_e32 v76, 16, v178
	v_and_b32_e32 v77, 0xffff0000, v178
	v_pk_mul_f32 v[76:77], v[86:87], v[76:77] op_sel_hi:[0,1]
	v_add_f32_e32 v0, 1.0, v0
	v_pk_mul_f32 v[76:77], v[118:119], v[76:77]
	v_pk_mul_f32 v[72:73], v[72:73], v[74:75]
	v_rcp_f32_e32 v74, v0
	v_add_f32_e32 v0, 1.0, v1
	v_pk_mul_f32 v[70:71], v[70:71], v[76:77]
	v_lshlrev_b32_e32 v76, 16, v179
	v_and_b32_e32 v77, 0xffff0000, v179
	v_rcp_f32_e32 v75, v0
	v_mul_f32_e32 v0, 0xbfb8aa3b, v68
	v_pk_mul_f32 v[76:77], v[86:87], v[76:77] op_sel_hi:[0,1]
	v_exp_f32_e32 v0, v0
	v_mul_f32_e32 v1, 0xbfb8aa3b, v69
	v_pk_mul_f32 v[76:77], v[120:121], v[76:77]
	v_exp_f32_e32 v1, v1
	v_pk_mul_f32 v[72:73], v[72:73], v[76:77]
	v_lshlrev_b32_e32 v76, 16, v180
	v_and_b32_e32 v77, 0xffff0000, v180
	v_pk_mul_f32 v[76:77], v[86:87], v[76:77] op_sel_hi:[0,1]
	v_pk_mul_f32 v[76:77], v[102:103], v[76:77]
	v_pk_mul_f32 v[66:67], v[66:67], v[74:75]
	v_add_f32_e32 v0, 1.0, v0
	v_pk_mul_f32 v[74:75], v[66:67], v[76:77]
	v_rcp_f32_e32 v66, v0
	v_add_f32_e32 v0, 1.0, v1
	v_rcp_f32_e32 v67, v0
	v_mul_f32_e32 v0, 0xbfb8aa3b, v62
	v_lshlrev_b32_e32 v76, 16, v181
	v_and_b32_e32 v77, 0xffff0000, v181
	v_exp_f32_e32 v0, v0
	v_mul_f32_e32 v1, 0xbfb8aa3b, v63
	v_pk_mul_f32 v[76:77], v[86:87], v[76:77] op_sel_hi:[0,1]
	v_exp_f32_e32 v1, v1
	v_pk_mul_f32 v[76:77], v[104:105], v[76:77]
	v_pk_mul_f32 v[66:67], v[68:69], v[66:67]
	v_cvt_pk_bf16_f32 v68, v74, v75
	v_pk_mul_f32 v[76:77], v[66:67], v[76:77]
	v_cvt_pk_bf16_f32 v66, v70, v71
	v_cvt_pk_bf16_f32 v67, v72, v73
	v_cvt_pk_bf16_f32 v69, v76, v77
	v_add_f32_e32 v0, 1.0, v0
	global_store_dwordx4 v[78:79], v[66:69], off offset:256
	ds_read2_b32 v[66:67], v222 offset0:128 offset1:144
	v_lshlrev_b32_e32 v70, 16, v174
	v_rcp_f32_e32 v68, v0
	v_add_f32_e32 v0, 1.0, v1
	v_rcp_f32_e32 v69, v0
	v_mul_f32_e32 v0, 0xbfb8aa3b, v64
	v_exp_f32_e32 v0, v0
	v_mul_f32_e32 v1, 0xbfb8aa3b, v65
	v_exp_f32_e32 v1, v1
	v_pk_mul_f32 v[62:63], v[62:63], v[68:69]
	v_add_f32_e32 v0, 1.0, v0
	v_rcp_f32_e32 v68, v0
	v_add_f32_e32 v0, 1.0, v1
	v_rcp_f32_e32 v69, v0
	v_mul_f32_e32 v0, 0xbfb8aa3b, v58
	v_exp_f32_e32 v0, v0
	v_mul_f32_e32 v1, 0xbfb8aa3b, v59
	v_exp_f32_e32 v1, v1
	v_and_b32_e32 v71, 0xffff0000, v174
	s_waitcnt lgkmcnt(0)
	v_pk_mul_f32 v[70:71], v[66:67], v[70:71] op_sel_hi:[0,1]
	v_add_f32_e32 v0, 1.0, v0
	v_pk_mul_f32 v[70:71], v[110:111], v[70:71]
	v_pk_mul_f32 v[64:65], v[64:65], v[68:69]
	v_rcp_f32_e32 v68, v0
	v_add_f32_e32 v0, 1.0, v1
	v_pk_mul_f32 v[62:63], v[62:63], v[70:71]
	v_lshlrev_b32_e32 v70, 16, v175
	v_and_b32_e32 v71, 0xffff0000, v175
	v_rcp_f32_e32 v69, v0
	v_mul_f32_e32 v0, 0xbfb8aa3b, v60
	v_pk_mul_f32 v[70:71], v[66:67], v[70:71] op_sel_hi:[0,1]
	v_exp_f32_e32 v0, v0
	v_mul_f32_e32 v1, 0xbfb8aa3b, v61
	v_pk_mul_f32 v[70:71], v[112:113], v[70:71]
	v_exp_f32_e32 v1, v1
	v_pk_mul_f32 v[64:65], v[64:65], v[70:71]
	v_lshlrev_b32_e32 v70, 16, v176
	v_and_b32_e32 v71, 0xffff0000, v176
	v_pk_mul_f32 v[70:71], v[66:67], v[70:71] op_sel_hi:[0,1]
	v_pk_mul_f32 v[70:71], v[94:95], v[70:71]
	v_pk_mul_f32 v[58:59], v[58:59], v[68:69]
	v_add_f32_e32 v0, 1.0, v0
	v_pk_mul_f32 v[68:69], v[58:59], v[70:71]
	v_rcp_f32_e32 v58, v0
	v_add_f32_e32 v0, 1.0, v1
	v_rcp_f32_e32 v59, v0
	v_mul_f32_e32 v0, 0xbfb8aa3b, v54
	v_lshlrev_b32_e32 v70, 16, v177
	v_and_b32_e32 v71, 0xffff0000, v177
	v_exp_f32_e32 v0, v0
	v_mul_f32_e32 v1, 0xbfb8aa3b, v55
	v_pk_mul_f32 v[70:71], v[66:67], v[70:71] op_sel_hi:[0,1]
	v_exp_f32_e32 v1, v1
	v_pk_mul_f32 v[70:71], v[96:97], v[70:71]
	v_pk_mul_f32 v[58:59], v[60:61], v[58:59]
	v_cvt_pk_bf16_f32 v60, v68, v69
	v_pk_mul_f32 v[70:71], v[58:59], v[70:71]
	v_cvt_pk_bf16_f32 v58, v62, v63
	v_lshl_add_u64 v[62:63], s[4:5], 0, v[210:211]
	v_cvt_pk_bf16_f32 v59, v64, v65
	v_cvt_pk_bf16_f32 v61, v70, v71
	v_lshl_add_u64 v[62:63], v[62:63], 0, v[202:203]
	v_add_f32_e32 v0, 1.0, v0
	global_store_dwordx4 v[62:63], v[58:61], off
	s_nop 1
	v_rcp_f32_e32 v58, v0
	v_add_f32_e32 v0, 1.0, v1
	v_rcp_f32_e32 v59, v0
	v_mul_f32_e32 v0, 0xbfb8aa3b, v56
	v_exp_f32_e32 v0, v0
	v_mul_f32_e32 v1, 0xbfb8aa3b, v57
	v_exp_f32_e32 v1, v1
	v_pk_mul_f32 v[54:55], v[54:55], v[58:59]
	v_add_f32_e32 v0, 1.0, v0
	v_rcp_f32_e32 v58, v0
	v_add_f32_e32 v0, 1.0, v1
	v_rcp_f32_e32 v59, v0
	v_mul_f32_e32 v0, 0xbfb8aa3b, v50
	v_exp_f32_e32 v0, v0
	v_mul_f32_e32 v1, 0xbfb8aa3b, v51
	v_exp_f32_e32 v1, v1
	v_lshlrev_b32_e32 v60, 16, v170
	v_and_b32_e32 v61, 0xffff0000, v170
	v_pk_mul_f32 v[60:61], v[66:67], v[60:61] op_sel_hi:[0,1]
	v_add_f32_e32 v0, 1.0, v0
	v_pk_mul_f32 v[60:61], v[118:119], v[60:61]
	v_pk_mul_f32 v[56:57], v[56:57], v[58:59]
	v_rcp_f32_e32 v58, v0
	v_add_f32_e32 v0, 1.0, v1
	v_pk_mul_f32 v[54:55], v[54:55], v[60:61]
	v_lshlrev_b32_e32 v60, 16, v171
	v_and_b32_e32 v61, 0xffff0000, v171
	v_rcp_f32_e32 v59, v0
	v_mul_f32_e32 v0, 0xbfb8aa3b, v52
	v_pk_mul_f32 v[60:61], v[66:67], v[60:61] op_sel_hi:[0,1]
	v_exp_f32_e32 v0, v0
	v_mul_f32_e32 v1, 0xbfb8aa3b, v53
	v_pk_mul_f32 v[60:61], v[120:121], v[60:61]
	v_exp_f32_e32 v1, v1
	v_pk_mul_f32 v[56:57], v[56:57], v[60:61]
	v_lshlrev_b32_e32 v60, 16, v172
	v_and_b32_e32 v61, 0xffff0000, v172
	v_pk_mul_f32 v[60:61], v[66:67], v[60:61] op_sel_hi:[0,1]
	v_pk_mul_f32 v[60:61], v[102:103], v[60:61]
	v_pk_mul_f32 v[50:51], v[50:51], v[58:59]
	v_add_f32_e32 v0, 1.0, v0
	v_pk_mul_f32 v[58:59], v[50:51], v[60:61]
	v_rcp_f32_e32 v50, v0
	v_add_f32_e32 v0, 1.0, v1
	v_rcp_f32_e32 v51, v0
	v_mul_f32_e32 v0, 0xbfb8aa3b, v46
	v_lshlrev_b32_e32 v60, 16, v173
	v_and_b32_e32 v61, 0xffff0000, v173
	v_exp_f32_e32 v0, v0
	v_mul_f32_e32 v1, 0xbfb8aa3b, v47
	v_pk_mul_f32 v[60:61], v[66:67], v[60:61] op_sel_hi:[0,1]
	v_exp_f32_e32 v1, v1
	v_pk_mul_f32 v[60:61], v[104:105], v[60:61]
	v_pk_mul_f32 v[50:51], v[52:53], v[50:51]
	v_cvt_pk_bf16_f32 v52, v58, v59
	v_pk_mul_f32 v[60:61], v[50:51], v[60:61]
	v_cvt_pk_bf16_f32 v50, v54, v55
	v_cvt_pk_bf16_f32 v51, v56, v57
	v_cvt_pk_bf16_f32 v53, v60, v61
	v_add_f32_e32 v0, 1.0, v0
	global_store_dwordx4 v[62:63], v[50:53], off offset:256
	v_mov_b32_e32 v54, v67
	s_nop 0
	v_rcp_f32_e32 v50, v0
	v_add_f32_e32 v0, 1.0, v1
	v_rcp_f32_e32 v51, v0
	v_mul_f32_e32 v0, 0xbfb8aa3b, v48
	v_exp_f32_e32 v0, v0
	v_mul_f32_e32 v1, 0xbfb8aa3b, v49
	v_exp_f32_e32 v1, v1
	v_pk_mul_f32 v[46:47], v[46:47], v[50:51]
	v_add_f32_e32 v0, 1.0, v0
	v_rcp_f32_e32 v50, v0
	v_add_f32_e32 v0, 1.0, v1
	v_rcp_f32_e32 v51, v0
	v_mul_f32_e32 v0, 0xbfb8aa3b, v42
	v_exp_f32_e32 v0, v0
	v_mul_f32_e32 v1, 0xbfb8aa3b, v43
	v_exp_f32_e32 v1, v1
	v_lshlrev_b32_e32 v52, 16, v166
	v_and_b32_e32 v53, 0xffff0000, v166
	v_pk_mul_f32 v[52:53], v[54:55], v[52:53] op_sel_hi:[0,1]
	v_add_f32_e32 v0, 1.0, v0
	v_pk_mul_f32 v[52:53], v[110:111], v[52:53]
	v_pk_mul_f32 v[48:49], v[48:49], v[50:51]
	v_rcp_f32_e32 v50, v0
	v_add_f32_e32 v0, 1.0, v1
	v_pk_mul_f32 v[46:47], v[46:47], v[52:53]
	v_lshlrev_b32_e32 v52, 16, v167
	v_and_b32_e32 v53, 0xffff0000, v167
	v_rcp_f32_e32 v51, v0
	v_mul_f32_e32 v0, 0xbfb8aa3b, v44
	v_pk_mul_f32 v[52:53], v[54:55], v[52:53] op_sel_hi:[0,1]
	v_exp_f32_e32 v0, v0
	v_mul_f32_e32 v1, 0xbfb8aa3b, v45
	v_pk_mul_f32 v[52:53], v[112:113], v[52:53]
	v_exp_f32_e32 v1, v1
	v_pk_mul_f32 v[48:49], v[48:49], v[52:53]
	v_lshlrev_b32_e32 v52, 16, v168
	v_and_b32_e32 v53, 0xffff0000, v168
	v_pk_mul_f32 v[52:53], v[54:55], v[52:53] op_sel_hi:[0,1]
	v_pk_mul_f32 v[52:53], v[94:95], v[52:53]
	v_pk_mul_f32 v[42:43], v[42:43], v[50:51]
	v_add_f32_e32 v0, 1.0, v0
	v_pk_mul_f32 v[50:51], v[42:43], v[52:53]
	v_rcp_f32_e32 v42, v0
	v_add_f32_e32 v0, 1.0, v1
	v_rcp_f32_e32 v43, v0
	v_mul_f32_e32 v0, 0xbfb8aa3b, v38
	v_lshlrev_b32_e32 v52, 16, v169
	v_and_b32_e32 v53, 0xffff0000, v169
	v_exp_f32_e32 v0, v0
	v_mul_f32_e32 v1, 0xbfb8aa3b, v39
	v_pk_mul_f32 v[52:53], v[54:55], v[52:53] op_sel_hi:[0,1]
	v_exp_f32_e32 v1, v1
	v_pk_mul_f32 v[52:53], v[96:97], v[52:53]
	v_pk_mul_f32 v[42:43], v[44:45], v[42:43]
	v_cvt_pk_bf16_f32 v44, v50, v51
	v_pk_mul_f32 v[52:53], v[42:43], v[52:53]
	v_cvt_pk_bf16_f32 v42, v46, v47
	v_lshl_add_u64 v[46:47], s[4:5], 0, v[208:209]
	v_cvt_pk_bf16_f32 v43, v48, v49
	v_cvt_pk_bf16_f32 v45, v52, v53
	v_lshl_add_u64 v[46:47], v[46:47], 0, v[202:203]
	v_add_f32_e32 v0, 1.0, v0
	global_store_dwordx4 v[46:47], v[42:45], off
	s_nop 1
	v_rcp_f32_e32 v42, v0
	v_add_f32_e32 v0, 1.0, v1
	v_rcp_f32_e32 v43, v0
	v_mul_f32_e32 v0, 0xbfb8aa3b, v40
	v_exp_f32_e32 v0, v0
	v_mul_f32_e32 v1, 0xbfb8aa3b, v41
	v_exp_f32_e32 v1, v1
	v_pk_mul_f32 v[38:39], v[38:39], v[42:43]
	v_add_f32_e32 v0, 1.0, v0
	v_rcp_f32_e32 v42, v0
	v_add_f32_e32 v0, 1.0, v1
	v_rcp_f32_e32 v43, v0
	v_mul_f32_e32 v0, 0xbfb8aa3b, v34
	v_exp_f32_e32 v0, v0
	v_mul_f32_e32 v1, 0xbfb8aa3b, v35
	v_exp_f32_e32 v1, v1
	v_lshlrev_b32_e32 v44, 16, v162
	v_and_b32_e32 v45, 0xffff0000, v162
	v_pk_mul_f32 v[44:45], v[54:55], v[44:45] op_sel_hi:[0,1]
	v_add_f32_e32 v0, 1.0, v0
	v_pk_mul_f32 v[44:45], v[118:119], v[44:45]
	v_pk_mul_f32 v[40:41], v[40:41], v[42:43]
	v_rcp_f32_e32 v42, v0
	v_add_f32_e32 v0, 1.0, v1
	v_pk_mul_f32 v[38:39], v[38:39], v[44:45]
	v_lshlrev_b32_e32 v44, 16, v163
	v_and_b32_e32 v45, 0xffff0000, v163
	v_rcp_f32_e32 v43, v0
	v_mul_f32_e32 v0, 0xbfb8aa3b, v36
	v_pk_mul_f32 v[44:45], v[54:55], v[44:45] op_sel_hi:[0,1]
	v_exp_f32_e32 v0, v0
	v_mul_f32_e32 v1, 0xbfb8aa3b, v37
	v_pk_mul_f32 v[44:45], v[120:121], v[44:45]
	v_exp_f32_e32 v1, v1
	v_pk_mul_f32 v[40:41], v[40:41], v[44:45]
	v_lshlrev_b32_e32 v44, 16, v164
	v_and_b32_e32 v45, 0xffff0000, v164
	v_pk_mul_f32 v[44:45], v[54:55], v[44:45] op_sel_hi:[0,1]
	v_pk_mul_f32 v[44:45], v[102:103], v[44:45]
	v_pk_mul_f32 v[34:35], v[34:35], v[42:43]
	v_add_f32_e32 v0, 1.0, v0
	v_pk_mul_f32 v[42:43], v[34:35], v[44:45]
	v_rcp_f32_e32 v34, v0
	v_add_f32_e32 v0, 1.0, v1
	v_rcp_f32_e32 v35, v0
	v_mul_f32_e32 v0, 0xbfb8aa3b, v30
	v_lshlrev_b32_e32 v44, 16, v165
	v_and_b32_e32 v45, 0xffff0000, v165
	v_exp_f32_e32 v0, v0
	v_mul_f32_e32 v1, 0xbfb8aa3b, v31
	v_pk_mul_f32 v[44:45], v[54:55], v[44:45] op_sel_hi:[0,1]
	v_exp_f32_e32 v1, v1
	v_pk_mul_f32 v[44:45], v[104:105], v[44:45]
	v_pk_mul_f32 v[34:35], v[36:37], v[34:35]
	v_cvt_pk_bf16_f32 v36, v42, v43
	v_pk_mul_f32 v[44:45], v[34:35], v[44:45]
	v_cvt_pk_bf16_f32 v34, v38, v39
	v_cvt_pk_bf16_f32 v35, v40, v41
	v_cvt_pk_bf16_f32 v37, v44, v45
	v_add_f32_e32 v0, 1.0, v0
	global_store_dwordx4 v[46:47], v[34:37], off offset:256
	ds_read2_b32 v[34:35], v222 offset0:160 offset1:176
	v_lshlrev_b32_e32 v38, 16, v150
	v_rcp_f32_e32 v36, v0
	v_add_f32_e32 v0, 1.0, v1
	v_rcp_f32_e32 v37, v0
	v_mul_f32_e32 v0, 0xbfb8aa3b, v32
	v_exp_f32_e32 v0, v0
	v_mul_f32_e32 v1, 0xbfb8aa3b, v33
	v_exp_f32_e32 v1, v1
	v_pk_mul_f32 v[30:31], v[30:31], v[36:37]
	v_add_f32_e32 v0, 1.0, v0
	v_rcp_f32_e32 v36, v0
	v_add_f32_e32 v0, 1.0, v1
	v_rcp_f32_e32 v37, v0
	v_mul_f32_e32 v0, 0xbfb8aa3b, v26
	v_exp_f32_e32 v0, v0
	v_mul_f32_e32 v1, 0xbfb8aa3b, v27
	v_exp_f32_e32 v1, v1
	v_and_b32_e32 v39, 0xffff0000, v150
	s_waitcnt lgkmcnt(0)
	v_pk_mul_f32 v[38:39], v[34:35], v[38:39] op_sel_hi:[0,1]
	v_add_f32_e32 v0, 1.0, v0
	v_pk_mul_f32 v[38:39], v[110:111], v[38:39]
	v_pk_mul_f32 v[32:33], v[32:33], v[36:37]
	v_rcp_f32_e32 v36, v0
	v_add_f32_e32 v0, 1.0, v1
	v_pk_mul_f32 v[30:31], v[30:31], v[38:39]
	v_lshlrev_b32_e32 v38, 16, v151
	v_and_b32_e32 v39, 0xffff0000, v151
	v_rcp_f32_e32 v37, v0
	v_mul_f32_e32 v0, 0xbfb8aa3b, v28
	v_pk_mul_f32 v[38:39], v[34:35], v[38:39] op_sel_hi:[0,1]
	v_exp_f32_e32 v0, v0
	v_mul_f32_e32 v1, 0xbfb8aa3b, v29
	v_pk_mul_f32 v[38:39], v[112:113], v[38:39]
	v_exp_f32_e32 v1, v1
	v_pk_mul_f32 v[32:33], v[32:33], v[38:39]
	v_lshlrev_b32_e32 v38, 16, v152
	v_and_b32_e32 v39, 0xffff0000, v152
	v_pk_mul_f32 v[38:39], v[34:35], v[38:39] op_sel_hi:[0,1]
	v_pk_mul_f32 v[38:39], v[94:95], v[38:39]
	v_pk_mul_f32 v[26:27], v[26:27], v[36:37]
	v_add_f32_e32 v0, 1.0, v0
	v_pk_mul_f32 v[36:37], v[26:27], v[38:39]
	v_rcp_f32_e32 v26, v0
	v_add_f32_e32 v0, 1.0, v1
	v_rcp_f32_e32 v27, v0
	v_mul_f32_e32 v0, 0xbfb8aa3b, v22
	v_lshlrev_b32_e32 v38, 16, v153
	v_and_b32_e32 v39, 0xffff0000, v153
	v_exp_f32_e32 v0, v0
	v_mul_f32_e32 v1, 0xbfb8aa3b, v23
	v_pk_mul_f32 v[38:39], v[34:35], v[38:39] op_sel_hi:[0,1]
	v_exp_f32_e32 v1, v1
	v_pk_mul_f32 v[38:39], v[96:97], v[38:39]
	v_pk_mul_f32 v[26:27], v[28:29], v[26:27]
	v_cvt_pk_bf16_f32 v28, v36, v37
	v_pk_mul_f32 v[38:39], v[26:27], v[38:39]
	v_cvt_pk_bf16_f32 v26, v30, v31
	v_lshl_add_u64 v[30:31], s[4:5], 0, v[206:207]
	v_cvt_pk_bf16_f32 v27, v32, v33
	v_cvt_pk_bf16_f32 v29, v38, v39
	v_lshl_add_u64 v[30:31], v[30:31], 0, v[202:203]
	v_add_f32_e32 v0, 1.0, v0
	global_store_dwordx4 v[30:31], v[26:29], off
	s_nop 1
	v_rcp_f32_e32 v26, v0
	v_add_f32_e32 v0, 1.0, v1
	v_rcp_f32_e32 v27, v0
	v_mul_f32_e32 v0, 0xbfb8aa3b, v24
	v_exp_f32_e32 v0, v0
	v_mul_f32_e32 v1, 0xbfb8aa3b, v25
	v_exp_f32_e32 v1, v1
	v_pk_mul_f32 v[22:23], v[22:23], v[26:27]
	v_add_f32_e32 v0, 1.0, v0
	v_rcp_f32_e32 v26, v0
	v_add_f32_e32 v0, 1.0, v1
	v_rcp_f32_e32 v27, v0
	v_mul_f32_e32 v0, 0xbfb8aa3b, v18
	v_exp_f32_e32 v0, v0
	v_mul_f32_e32 v1, 0xbfb8aa3b, v19
	v_exp_f32_e32 v1, v1
	v_lshlrev_b32_e32 v28, 16, v142
	v_and_b32_e32 v29, 0xffff0000, v142
	v_pk_mul_f32 v[28:29], v[34:35], v[28:29] op_sel_hi:[0,1]
	v_add_f32_e32 v0, 1.0, v0
	v_pk_mul_f32 v[28:29], v[118:119], v[28:29]
	v_pk_mul_f32 v[24:25], v[24:25], v[26:27]
	v_rcp_f32_e32 v26, v0
	v_add_f32_e32 v0, 1.0, v1
	v_pk_mul_f32 v[22:23], v[22:23], v[28:29]
	v_lshlrev_b32_e32 v28, 16, v143
	v_and_b32_e32 v29, 0xffff0000, v143
	v_rcp_f32_e32 v27, v0
	v_mul_f32_e32 v0, 0xbfb8aa3b, v20
	v_pk_mul_f32 v[28:29], v[34:35], v[28:29] op_sel_hi:[0,1]
	v_exp_f32_e32 v0, v0
	v_mul_f32_e32 v1, 0xbfb8aa3b, v21
	v_pk_mul_f32 v[28:29], v[120:121], v[28:29]
	v_exp_f32_e32 v1, v1
	v_pk_mul_f32 v[24:25], v[24:25], v[28:29]
	v_lshlrev_b32_e32 v28, 16, v144
	v_and_b32_e32 v29, 0xffff0000, v144
	v_pk_mul_f32 v[28:29], v[34:35], v[28:29] op_sel_hi:[0,1]
	v_pk_mul_f32 v[28:29], v[102:103], v[28:29]
	v_pk_mul_f32 v[18:19], v[18:19], v[26:27]
	v_add_f32_e32 v0, 1.0, v0
	v_pk_mul_f32 v[26:27], v[18:19], v[28:29]
	v_rcp_f32_e32 v18, v0
	v_add_f32_e32 v0, 1.0, v1
	v_rcp_f32_e32 v19, v0
	v_mul_f32_e32 v0, 0xbfb8aa3b, v14
	v_lshlrev_b32_e32 v28, 16, v145
	v_and_b32_e32 v29, 0xffff0000, v145
	v_exp_f32_e32 v0, v0
	v_mul_f32_e32 v1, 0xbfb8aa3b, v15
	v_pk_mul_f32 v[28:29], v[34:35], v[28:29] op_sel_hi:[0,1]
	v_exp_f32_e32 v1, v1
	v_pk_mul_f32 v[28:29], v[104:105], v[28:29]
	v_pk_mul_f32 v[18:19], v[20:21], v[18:19]
	v_cvt_pk_bf16_f32 v20, v26, v27
	v_pk_mul_f32 v[28:29], v[18:19], v[28:29]
	v_cvt_pk_bf16_f32 v18, v22, v23
	v_cvt_pk_bf16_f32 v19, v24, v25
	v_cvt_pk_bf16_f32 v21, v28, v29
	v_add_f32_e32 v0, 1.0, v0
	global_store_dwordx4 v[30:31], v[18:21], off offset:256
	v_mov_b32_e32 v22, v35
	s_nop 0
	v_rcp_f32_e32 v18, v0
	v_add_f32_e32 v0, 1.0, v1
	v_rcp_f32_e32 v19, v0
	v_mul_f32_e32 v0, 0xbfb8aa3b, v16
	v_exp_f32_e32 v0, v0
	v_mul_f32_e32 v1, 0xbfb8aa3b, v17
	v_exp_f32_e32 v1, v1
	v_pk_mul_f32 v[14:15], v[14:15], v[18:19]
	v_add_f32_e32 v0, 1.0, v0
	v_rcp_f32_e32 v18, v0
	v_add_f32_e32 v0, 1.0, v1
	v_rcp_f32_e32 v19, v0
	v_mul_f32_e32 v0, 0xbfb8aa3b, v10
	v_exp_f32_e32 v0, v0
	v_mul_f32_e32 v1, 0xbfb8aa3b, v11
	v_exp_f32_e32 v1, v1
	v_lshlrev_b32_e32 v20, 16, v126
	v_and_b32_e32 v21, 0xffff0000, v126
	v_pk_mul_f32 v[20:21], v[22:23], v[20:21] op_sel_hi:[0,1]
	v_add_f32_e32 v0, 1.0, v0
	v_pk_mul_f32 v[20:21], v[110:111], v[20:21]
	v_pk_mul_f32 v[16:17], v[16:17], v[18:19]
	v_rcp_f32_e32 v18, v0
	v_add_f32_e32 v0, 1.0, v1
	v_pk_mul_f32 v[14:15], v[14:15], v[20:21]
	v_lshlrev_b32_e32 v20, 16, v127
	v_and_b32_e32 v21, 0xffff0000, v127
	v_rcp_f32_e32 v19, v0
	v_mul_f32_e32 v0, 0xbfb8aa3b, v12
	v_pk_mul_f32 v[20:21], v[22:23], v[20:21] op_sel_hi:[0,1]
	v_exp_f32_e32 v0, v0
	v_mul_f32_e32 v1, 0xbfb8aa3b, v13
	v_pk_mul_f32 v[20:21], v[112:113], v[20:21]
	v_exp_f32_e32 v1, v1
	v_pk_mul_f32 v[16:17], v[16:17], v[20:21]
	v_lshlrev_b32_e32 v20, 16, v128
	v_and_b32_e32 v21, 0xffff0000, v128
	v_pk_mul_f32 v[20:21], v[22:23], v[20:21] op_sel_hi:[0,1]
	v_pk_mul_f32 v[20:21], v[94:95], v[20:21]
	v_pk_mul_f32 v[10:11], v[10:11], v[18:19]
	v_add_f32_e32 v0, 1.0, v0
	v_pk_mul_f32 v[18:19], v[10:11], v[20:21]
	v_rcp_f32_e32 v10, v0
	v_add_f32_e32 v0, 1.0, v1
	v_rcp_f32_e32 v11, v0
	v_mul_f32_e32 v0, 0xbfb8aa3b, v6
	v_lshlrev_b32_e32 v20, 16, v129
	v_and_b32_e32 v21, 0xffff0000, v129
	v_exp_f32_e32 v0, v0
	v_mul_f32_e32 v1, 0xbfb8aa3b, v7
	v_pk_mul_f32 v[20:21], v[22:23], v[20:21] op_sel_hi:[0,1]
	v_exp_f32_e32 v1, v1
	v_pk_mul_f32 v[20:21], v[96:97], v[20:21]
	v_pk_mul_f32 v[10:11], v[12:13], v[10:11]
	v_cvt_pk_bf16_f32 v12, v18, v19
	v_pk_mul_f32 v[20:21], v[10:11], v[20:21]
	v_cvt_pk_bf16_f32 v10, v14, v15
	v_lshl_add_u64 v[14:15], s[4:5], 0, v[204:205]
	v_cvt_pk_bf16_f32 v11, v16, v17
	v_cvt_pk_bf16_f32 v13, v20, v21
	v_lshl_add_u64 v[14:15], v[14:15], 0, v[202:203]
	v_add_f32_e32 v0, 1.0, v0
	global_store_dwordx4 v[14:15], v[10:13], off
	s_sext_i32_i8 s4, s2
	s_and_b32 s2, s2, 0xf8
	v_rcp_f32_e32 v10, v0
	v_add_f32_e32 v0, 1.0, v1
	v_rcp_f32_e32 v11, v0
	v_mul_f32_e32 v0, 0xbfb8aa3b, v8
	v_exp_f32_e32 v0, v0
	v_mul_f32_e32 v1, 0xbfb8aa3b, v9
	v_exp_f32_e32 v1, v1
	v_pk_mul_f32 v[6:7], v[6:7], v[10:11]
	v_add_f32_e32 v0, 1.0, v0
	v_rcp_f32_e32 v10, v0
	v_add_f32_e32 v0, 1.0, v1
	v_rcp_f32_e32 v11, v0
	v_mul_f32_e32 v0, 0xbfb8aa3b, v2
	v_exp_f32_e32 v0, v0
	v_mul_f32_e32 v1, 0xbfb8aa3b, v3
	v_exp_f32_e32 v1, v1
	v_lshlrev_b32_e32 v12, 16, v114
	v_and_b32_e32 v13, 0xffff0000, v114
	v_pk_mul_f32 v[12:13], v[22:23], v[12:13] op_sel_hi:[0,1]
	v_add_f32_e32 v0, 1.0, v0
	v_pk_mul_f32 v[12:13], v[118:119], v[12:13]
	v_pk_mul_f32 v[8:9], v[8:9], v[10:11]
	v_rcp_f32_e32 v10, v0
	v_add_f32_e32 v0, 1.0, v1
	v_pk_mul_f32 v[6:7], v[6:7], v[12:13]
	v_lshlrev_b32_e32 v12, 16, v115
	v_and_b32_e32 v13, 0xffff0000, v115
	v_rcp_f32_e32 v11, v0
	v_mul_f32_e32 v0, 0xbfb8aa3b, v4
	v_pk_mul_f32 v[12:13], v[22:23], v[12:13] op_sel_hi:[0,1]
	v_exp_f32_e32 v0, v0
	v_mul_f32_e32 v1, 0xbfb8aa3b, v5
	v_pk_mul_f32 v[12:13], v[120:121], v[12:13]
	v_exp_f32_e32 v1, v1
	v_pk_mul_f32 v[8:9], v[8:9], v[12:13]
	v_lshlrev_b32_e32 v12, 16, v116
	v_and_b32_e32 v13, 0xffff0000, v116
	v_pk_mul_f32 v[12:13], v[22:23], v[12:13] op_sel_hi:[0,1]
	s_sub_i32 s2, s0, s2
	v_pk_mul_f32 v[12:13], v[102:103], v[12:13]
	v_pk_mul_f32 v[2:3], v[2:3], v[10:11]
	v_add_f32_e32 v0, 1.0, v0
	s_sext_i32_i8 s2, s2
	v_pk_mul_f32 v[10:11], v[2:3], v[12:13]
	v_rcp_f32_e32 v2, v0
	v_add_f32_e32 v0, 1.0, v1
	s_add_i32 s2, s1, s2
	v_rcp_f32_e32 v3, v0
	v_writelane_b32 v255, s2, 23
	s_ashr_i32 s1, s4, 3
	v_lshlrev_b32_e32 v12, 16, v117
	v_writelane_b32 v255, s3, 24
	s_lshl_b32 s2, s1, 2
	v_and_b32_e32 v13, 0xffff0000, v117
	s_and_b32 s2, s2, 4
	s_ashr_i32 s4, s4, 4
	v_pk_mul_f32 v[12:13], v[22:23], v[12:13] op_sel_hi:[0,1]
	s_add_i32 s2, s2, s4
	v_pk_mul_f32 v[12:13], v[104:105], v[12:13]
	v_pk_mul_f32 v[2:3], v[4:5], v[2:3]
	s_cmp_lt_i32 s0, 64
	v_pk_mul_f32 v[12:13], v[2:3], v[12:13]
	s_cselect_b32 s64, s2, s1
	s_add_i32 s0, 0, 0x24ef0
	v_cvt_pk_bf16_f32 v2, v6, v7
	v_cvt_pk_bf16_f32 v3, v8, v9
	v_cvt_pk_bf16_f32 v4, v10, v11
	v_cvt_pk_bf16_f32 v5, v12, v13
	v_mov_b32_e32 v0, s0
	s_add_i32 s0, 0, 0x24ef4
	global_store_dwordx4 v[14:15], v[2:5], off offset:256
	s_waitcnt vmcnt(0)
	s_barrier
; DEV int opaque_tid() { int t = threadIdx.x; asm volatile("" : "+v"(t)); return t; }
; #define G8_STAGE(bufoff, gbase, voff) do { _Pragma("unroll") for (int _i = 0; _i < 2; ++_i) \
;         __builtin_amdgcn_global_load_lds((const unsigned*)((const char*)(gbase) + (voff)[_i]), (LAS unsigned*)(lds + (bufoff) + ldsw + _i * 8192), 16, 0, 0); } while (0)
; #define G8_BAR __builtin_amdgcn_s_barrier()
; template <class Epi, class Sched>
; DEV void gemm_phase(LAS char* lds, const Sched& S, const Epi& E) {
;     const int tid = opaque_tid(), wid = __builtin_amdgcn_readfirstlane(tid >> 6), lane = tid & 63, wr = wid >> 2, wc = wid & 3, fr = lane & 15, fq = lane >> 4;
;     constexpr int lda = Sched::lda, ldb = Sched::ldb, nt = Sched::K / BK;
;     unsigned voffA[2], voffB[2];
; #pragma unroll
;     for (int i = 0; i < 2; ++i) { int R, C; stage_rc(tid * 16 + i * 8192, R, C); const int Rb = (R & ~31) + perm32(R & 31);
;         voffA[i] = Sched::aoff(R, C); voffB[i] = (unsigned)(Rb * ldb + C) * 2u; asm volatile("" : "+v"(voffA[i]), "+v"(voffB[i])); }
;     constexpr size_t kstep = (size_t)(BK * 2), kstepA = Sched::kstepA, hstepA = Sched::hstepA, hstepB = Sched::hstepB;
;     const unsigned ldsw = (unsigned)wid * 1024u;
;     const int aoff = lds_byte(wr * 64 + fr, fq * 8), boff = lds_byte(wc * 32 + fr, fq * 8);
;     ...
;     Unit cur, nxt; int ui = 0;
;     __syncthreads();
;     if (!S.next(0, cur)) return;
;     f32x4 acc[2][2][4][2];
; #pragma unroll
;     for (int a = 0; a < 2; ++a)
; #pragma unroll
;         for (int b = 0; b < 2; ++b)
; #pragma unroll
;             for (int m = 0; m < 4; ++m)
; #pragma unroll
;                 for (int n = 0; n < 2; ++n) acc[a][b][m][n] = (f32x4){0.f, 0.f, 0.f, 0.f};
;     bf16x8 At[4][2], B0[2][2], B1[2][2];
;     const char* cA = cur.A; const char* cA2 = cur.A2; const char* cB = cur.B;
;     constexpr int KSP = Sched::ksplit;
;     ...
;     G8_STAGE(G8_SB(0, 0), cB, voffB); G8_STAGE(G8_SB(0, 1), cB + hstepB, voffB); G8_STAGE(G8_SA(0, 0), cA, voffA); G8_STAGE(G8_SA(0, 1), cA + hstepA, voffA);
;     if (wr == 1) G8_BAR;
	ds_read_b32 v1, v0
	v_mov_b32_e32 v2, s0
	ds_read_b32 v3, v2
	v_mov_b32_e32 v10, v254
	v_writelane_b32 v255, s16, 25
	s_waitcnt lgkmcnt(1)
	v_readfirstlane_b32 s2, v1
	s_and_b64 vcc, exec, s[16:17]
	s_waitcnt lgkmcnt(0)
	v_readfirstlane_b32 s4, v3
	ds_read_b32 v1, v0
	ds_read_b32 v3, v2
	ds_read_b32 v4, v0
	ds_read_b32 v5, v2
	ds_read_b32 v6, v0
	s_waitcnt lgkmcnt(4)
	v_readfirstlane_b32 s5, v1
	s_waitcnt lgkmcnt(3)
	v_readfirstlane_b32 s9, v3
	s_waitcnt lgkmcnt(2)
	v_readfirstlane_b32 s10, v4
	ds_read_b32 v1, v2
	ds_read_b32 v3, v0
	ds_read_b32 v4, v2
	ds_read_b32 v0, v0
	ds_read_b32 v2, v2
	s_waitcnt lgkmcnt(6)
	v_readfirstlane_b32 s11, v5
	s_waitcnt lgkmcnt(2)
	v_readfirstlane_b32 s6, v4
	s_waitcnt lgkmcnt(1)
	v_readfirstlane_b32 s7, v0
	v_lshlrev_b32_e32 v0, 4, v10
	s_waitcnt lgkmcnt(0)
	v_readfirstlane_b32 s8, v2
	v_bfe_u32 v2, v0, 6, 4
	v_ashrrev_i32_e32 v4, 3, v10
	v_readfirstlane_b32 s12, v6
	v_and_or_b32 v5, v4, s14, v2
	v_and_b32_e32 v6, 0x7fffe0, v4
	v_lshrrev_b32_e32 v4, 2, v4
	v_readfirstlane_b32 s13, v1
	v_and_b32_e32 v1, 32, v10
	v_and_or_b32 v4, v4, 4, v6
	v_lshrrev_b32_e32 v6, 1, v10
	v_readfirstlane_b32 s1, v3
	v_bitop3_b32 v1, v0, v1, 48 bitop3:0x6c
	v_bfe_u32 v3, v0, 6, 2
	v_and_b32_e32 v6, 24, v6
	v_add_u32_e32 v0, 0x2000, v0
	v_and_or_b32 v1, v10, 64, v1
	v_or3_b32 v4, v4, v6, v3
	v_ashrrev_i32_e32 v0, 7, v0
	v_lshl_or_b32 v132, v4, 9, v1
	v_lshrrev_b32_e32 v4, 2, v0
	v_and_b32_e32 v4, 4, v4
	v_and_or_b32 v2, v0, s14, v2
	v_and_or_b32 v0, v0, s15, v4
	v_or3_b32 v0, v0, v6, v3
	v_readfirstlane_b32 s0, v10
	v_lshl_or_b32 v130, v5, 11, v1
	v_lshl_or_b32 v134, v2, 11, v1
	v_lshl_or_b32 v136, v0, 9, v1
	v_writelane_b32 v255, s17, 26
	s_barrier
	s_cbranch_vccz .LBB0_532
	s_add_u32 s2, s2, 0x8048000
	s_addc_u32 s44, s4, 0
	s_add_u32 s45, s5, 0xa05a000
	s_addc_u32 s46, s9, 0
	v_readlane_b32 s14, v255, 23
	s_add_u32 s47, s10, 0xec7e000
	v_readlane_b32 s15, v255, 24
	s_addc_u32 s54, s11, 0
	s_ashr_i32 s10, s0, 6
	s_ashr_i32 s65, s64, 31
	s_mov_b32 s16, s14
	s_ashr_i32 s17, s14, 31
	v_writelane_b32 v255, s14, 23
	s_ashr_i32 s9, s0, 8
	s_lshl_b32 s55, s10, 10
	s_lshl_b64 s[4:5], s[64:65], 17
	v_writelane_b32 v255, s15, 24
	s_lshl_b64 s[14:15], s[16:17], 19
	s_and_b32 s11, s64, -4
	s_cmp_eq_u32 s11, 8
	s_cselect_b32 s16, s45, s2
	s_cselect_b32 s11, s46, s44
	s_add_u32 s14, s16, s14
	s_addc_u32 s11, s11, s15
	s_lshl_b32 s15, s64, 9
	s_and_b32 s15, s15, 0x600
	s_add_u32 s24, s14, s15
	s_addc_u32 s25, s11, 0
	s_add_u32 s26, s47, s4
	s_addc_u32 s27, s54, s5
	s_add_i32 s56, s55, 0
	s_add_i32 m0, s56, 0x10000
	v_mov_b32_e32 v139, 0
	global_load_lds_dwordx4 v132, s[26:27]
	s_add_i32 m0, s56, 0x12000
	s_add_u32 s4, s26, 0x10000
	global_load_lds_dwordx4 v136, s[26:27]
	s_addc_u32 s5, s27, 0
	s_add_i32 m0, s56, 0x14000
	s_add_i32 s57, s56, 0x2000
	global_load_lds_dwordx4 v132, s[4:5]
	s_add_i32 m0, s56, 0x16000
	v_mov_b32_e32 v133, v139
	global_load_lds_dwordx4 v136, s[4:5]
	s_mov_b32 m0, s56
	s_add_u32 s4, s24, 0x40000
	global_load_lds_dwordx4 v130, s[24:25]
	s_mov_b32 m0, s57
	s_addc_u32 s5, s25, 0
	s_add_i32 s60, s56, 0x4000
	global_load_lds_dwordx4 v134, s[24:25]
	s_mov_b32 m0, s60
	s_add_i32 s61, s56, 0x6000
	global_load_lds_dwordx4 v130, s[4:5]
	s_mov_b32 m0, s61
	v_mov_b32_e32 v137, v139
	global_load_lds_dwordx4 v134, s[4:5]
	v_mov_b32_e32 v131, v139
	v_mov_b32_e32 v135, v139
	s_cmp_eq_u32 s9, 1
	v_lshl_add_u64 v[8:9], s[26:27], 0, v[132:133]
	v_lshl_add_u64 v[6:7], s[26:27], 0, v[136:137]
	v_lshl_add_u64 v[2:3], s[24:25], 0, v[130:131]
	s_cselect_b64 s[4:5], -1, 0
	s_cmp_lg_u32 s9, 1
	v_lshl_add_u64 v[4:5], s[24:25], 0, v[134:135]
	s_cbranch_scc1 .LBB0_515
	s_barrier

.LBB0_1362:
	s_or_b64 exec, exec, s[6:7]
	s_movk_i32 s0, 0x100
	v_cmp_gt_i32_e32 vcc, s0, v99
	s_barrier
	v_mov_b32_e32 v234, v99
	s_and_saveexec_b64 s[0:1], vcc
	v_readlane_b32 s6, v255, 22
	s_cbranch_execz .Lg2s1_a
	s_nop 0
	v_add_u32_e32 v232, s6, v99
	v_ashrrev_i32_e32 v233, 31, v232
	v_lshl_add_u64 v[232:233], v[232:233], 4, s[8:9]
	global_load_dword v235, v[232:233], off sc1
	global_load_dword v236, v[232:233], off offset:4 sc1
	global_load_dword v237, v[232:233], off offset:8 sc1
	s_nop 0
	global_load_dword v232, v[232:233], off offset:12 sc1
.Lg2s1_a:
	s_or_b64 exec, exec, s[0:1]
	s_add_u32 s4, s24, 0x6036000
	v_readlane_b32 s0, v255, 21
	s_addc_u32 s5, s25, 0
	s_or_b32 s0, s27, s0
	v_lshl_add_u32 v98, v98, 3, s0
	v_add_u32_e32 v100, s26, v114
	v_ashrrev_i32_e32 v99, 31, v98
	v_add_u32_e32 v110, s6, v100
	v_lshlrev_b64 v[202:203], 1, v[98:99]
	v_ashrrev_i32_e32 v111, 31, v110
	v_mov_b32_e32 v0, s22
	v_mov_b32_e32 v1, s23
	v_lshl_add_u64 v[112:113], s[4:5], 0, v[202:203]
	v_lshlrev_b64 v[218:219], 11, v[110:111]
	v_lshl_add_u64 v[0:1], v[98:99], 2, v[0:1]
	v_lshl_add_u64 v[114:115], v[112:113], 0, v[218:219]
	s_movk_i32 s0, 0x1000
	global_load_dwordx4 v[198:201], v[114:115], off
	global_load_dwordx4 v[224:227], v[114:115], off offset:256
	v_add_co_u32_e32 v98, vcc, s0, v0
	s_mov_b64 s[0:1], 0x1000
	s_nop 0
	v_addc_co_u32_e32 v99, vcc, 0, v1, vcc
	global_load_dwordx4 v[106:109], v[98:99], off
	v_mul_f32_e32 v98, 0xbfb8aa3b, v158
	v_mul_f32_e32 v99, 0xbfb8aa3b, v159
	v_mul_f32_e32 v101, 0xbfb8aa3b, v160
	v_lshl_add_u64 v[0:1], v[0:1], 0, s[0:1]
	v_lshl_add_u32 v111, v100, 2, 0
	v_exp_f32_e32 v144, v98
	v_exp_f32_e32 v145, v99
	v_exp_f32_e32 v223, v101
	global_load_dwordx4 v[98:101], v[0:1], off offset:16
	v_add_u32_e32 v118, 32, v110
	v_ashrrev_i32_e32 v119, 31, v118
	v_lshlrev_b64 v[214:215], 11, v[118:119]
	v_add_f32_e32 v118, 1.0, v144
	v_add_f32_e32 v150, 1.0, v145
	v_add_u32_e32 v222, 0x21000, v111
	v_rcp_f32_e32 v114, v118
	v_rcp_f32_e32 v115, v150
	v_add_u32_e32 v116, 16, v110
	v_add_u32_e32 v120, 48, v110
	v_add_u32_e32 v126, 0x80, v110
	v_add_u32_e32 v128, 0x90, v110
	v_add_u32_e32 v142, 0xa0, v110
	v_add_u32_e32 v110, 0xb0, v110
	s_nop 0
	v_ashrrev_i32_e32 v117, 31, v116
	v_ashrrev_i32_e32 v121, 31, v120
	v_ashrrev_i32_e32 v127, 31, v126
	v_ashrrev_i32_e32 v129, 31, v128
	v_ashrrev_i32_e32 v143, 31, v142
	v_ashrrev_i32_e32 v111, 31, v110
	v_lshlrev_b64 v[216:217], 11, v[116:117]
	v_lshlrev_b64 v[212:213], 11, v[120:121]
	v_lshlrev_b64 v[210:211], 11, v[126:127]
	v_lshlrev_b64 v[208:209], 11, v[128:129]
	v_lshlrev_b64 v[206:207], 11, v[142:143]
	v_lshlrev_b64 v[204:205], 11, v[110:111]
	v_lshl_add_u64 v[110:111], v[112:113], 0, v[216:217]
	v_lshl_add_u64 v[116:117], v[112:113], 0, v[214:215]
	v_lshl_add_u64 v[126:127], v[112:113], 0, v[212:213]
	v_lshl_add_u64 v[128:129], v[112:113], 0, v[210:211]
	v_lshl_add_u64 v[142:143], v[112:113], 0, v[208:209]
	v_lshl_add_u64 v[144:145], v[112:113], 0, v[206:207]
	v_lshl_add_u64 v[112:113], v[112:113], 0, v[204:205]
	global_load_dwordx4 v[118:121], v[0:1], off offset:512
	v_pk_mul_f32 v[114:115], v[158:159], v[114:115]
	v_mul_f32_e32 v158, 0xbfb8aa3b, v161
	global_load_dwordx4 v[228:231], v[110:111], off
	global_load_dwordx4 v[194:197], v[110:111], off offset:256
	global_load_dwordx4 v[190:193], v[116:117], off
	global_load_dwordx4 v[186:189], v[116:117], off offset:256
	global_load_dwordx4 v[182:185], v[126:127], off
	global_load_dwordx4 v[178:181], v[126:127], off offset:256
	global_load_dwordx4 v[174:177], v[128:129], off
	global_load_dwordx4 v[170:173], v[128:129], off offset:256
	global_load_dwordx4 v[166:169], v[142:143], off
	global_load_dwordx4 v[162:165], v[142:143], off offset:256
	global_load_dwordx4 v[150:153], v[144:145], off
	s_nop 0
	global_load_dwordx4 v[142:145], v[144:145], off offset:256
	s_nop 0
	global_load_dwordx4 v[126:129], v[112:113], off
	s_nop 0
	global_load_dwordx4 v[110:113], v[112:113], off offset:256
	s_add_i32 s0, 0, 0x24ef0
	s_mov_b32 s14, 0x1ffff0
	s_mov_b32 s15, 0x7fffe0
	s_movk_i32 s100, 0x100
	v_cmp_gt_i32_e32 vcc, s100, v234
	s_and_saveexec_b64 s[98:99], vcc
	s_cbranch_execz .Lg2s1_b
	v_mov_b32_e32 v233, 0x358637bd
	s_mov_b32 s100, 0x800000
	s_waitcnt vmcnt(19)
	v_add_f32_e32 v235, v236, v235
	v_add_f32_e32 v235, v235, v237
	v_add_f32_e32 v232, v235, v232
	v_fmac_f32_e32 v233, 0x3a800000, v232
	v_mul_f32_e32 v232, 0x4b800000, v233
	v_cmp_gt_f32_e32 vcc, s100, v233
	s_nop 1
	v_cndmask_b32_e32 v232, v233, v232, vcc
	v_rsq_f32_e32 v232, v232
	v_lshl_add_u32 v233, v234, 2, 0
	v_add_u32_e32 v233, 0x21000, v233
	v_mul_f32_e32 v238, 0x45800000, v232
	v_cndmask_b32_e32 v232, v232, v238, vcc
	ds_write_b32 v233, v232
.Lg2s1_b:
	s_or_b64 exec, exec, s[98:99]
	s_waitcnt lgkmcnt(0)
	s_barrier
	ds_read2_b32 v[220:221], v222 offset1:16
	s_waitcnt vmcnt(0)
	v_lshlrev_b32_e32 v116, 16, v198
	v_and_b32_e32 v117, 0xffff0000, v198
	v_exp_f32_e32 v198, v158
	s_waitcnt lgkmcnt(0)
	v_pk_mul_f32 v[116:117], v[220:221], v[116:117] op_sel_hi:[0,1]
	v_pk_mul_f32 v[116:117], v[106:107], v[116:117]
	s_nop 0
	v_pk_mul_f32 v[158:159], v[114:115], v[116:117]
	v_add_f32_e32 v114, 1.0, v223
	v_rcp_f32_e32 v232, v114
	v_add_f32_e32 v114, 1.0, v198
	v_rcp_f32_e32 v233, v114
	global_load_dwordx4 v[114:117], v[0:1], off offset:528
	v_lshlrev_b32_e32 v0, 16, v199
	v_and_b32_e32 v1, 0xffff0000, v199
	v_mul_f32_e32 v198, 0xbfb8aa3b, v154
	v_mul_f32_e32 v199, 0xbfb8aa3b, v155
	v_exp_f32_e32 v198, v198
	v_exp_f32_e32 v199, v199
	v_pk_mul_f32 v[0:1], v[220:221], v[0:1] op_sel_hi:[0,1]
	v_pk_mul_f32 v[0:1], v[108:109], v[0:1]
	v_pk_mul_f32 v[160:161], v[160:161], v[232:233]
	s_nop 0
	v_pk_mul_f32 v[0:1], v[160:161], v[0:1]
	v_add_f32_e32 v160, 1.0, v198
	v_add_f32_e32 v161, 1.0, v199
	v_rcp_f32_e32 v160, v160
	v_rcp_f32_e32 v161, v161
	v_lshlrev_b32_e32 v198, 16, v200
	v_and_b32_e32 v199, 0xffff0000, v200
	v_pk_mul_f32 v[198:199], v[220:221], v[198:199] op_sel_hi:[0,1]
	v_pk_mul_f32 v[154:155], v[154:155], v[160:161]
	v_mul_f32_e32 v160, 0xbfb8aa3b, v156
	v_exp_f32_e32 v200, v160
	v_mul_f32_e32 v160, 0xbfb8aa3b, v157
	v_exp_f32_e32 v223, v160
	v_pk_mul_f32 v[198:199], v[98:99], v[198:199]
	s_nop 0
	v_pk_mul_f32 v[160:161], v[154:155], v[198:199]
	v_add_f32_e32 v154, 1.0, v200
	v_add_f32_e32 v155, 1.0, v223
	v_rcp_f32_e32 v154, v154
	v_rcp_f32_e32 v155, v155
	v_lshlrev_b32_e32 v198, 16, v201
	v_and_b32_e32 v199, 0xffff0000, v201
	v_pk_mul_f32 v[198:199], v[220:221], v[198:199] op_sel_hi:[0,1]
	v_pk_mul_f32 v[198:199], v[100:101], v[198:199]
	v_pk_mul_f32 v[154:155], v[156:157], v[154:155]
	v_cvt_pk_bf16_f32 v156, v160, v161
	v_pk_mul_f32 v[198:199], v[154:155], v[198:199]
	v_cvt_pk_bf16_f32 v154, v158, v159
	v_mul_f32_e32 v158, 0xbfb8aa3b, v146
	v_mul_f32_e32 v159, 0xbfb8aa3b, v147
	v_exp_f32_e32 v158, v158
	v_exp_f32_e32 v159, v159
	v_lshlrev_b32_e32 v160, 16, v224
	v_and_b32_e32 v161, 0xffff0000, v224
	v_add_f32_e32 v158, 1.0, v158
	v_add_f32_e32 v159, 1.0, v159
	v_rcp_f32_e32 v158, v158
	v_rcp_f32_e32 v159, v159
	v_pk_mul_f32 v[160:161], v[220:221], v[160:161] op_sel_hi:[0,1]
	v_pk_mul_f32 v[160:161], v[118:119], v[160:161]
	v_cvt_pk_bf16_f32 v157, v198, v199
	v_pk_mul_f32 v[146:147], v[146:147], v[158:159]
	v_mul_f32_e32 v158, 0xbfb8aa3b, v148
	v_mul_f32_e32 v159, 0xbfb8aa3b, v149
	v_exp_f32_e32 v158, v158
	v_exp_f32_e32 v159, v159
	v_pk_mul_f32 v[146:147], v[146:147], v[160:161]
	v_lshlrev_b32_e32 v160, 16, v225
	v_add_f32_e32 v158, 1.0, v158
	v_add_f32_e32 v159, 1.0, v159
	v_rcp_f32_e32 v158, v158
	v_rcp_f32_e32 v159, v159
	v_and_b32_e32 v161, 0xffff0000, v225
	v_pk_mul_f32 v[160:161], v[220:221], v[160:161] op_sel_hi:[0,1]
	v_pk_mul_f32 v[160:161], v[120:121], v[160:161]
	v_pk_mul_f32 v[148:149], v[148:149], v[158:159]
	v_mul_f32_e32 v158, 0xbfb8aa3b, v138
	v_mul_f32_e32 v159, 0xbfb8aa3b, v139
	v_exp_f32_e32 v158, v158
	v_exp_f32_e32 v159, v159
	v_pk_mul_f32 v[148:149], v[148:149], v[160:161]
	v_lshlrev_b32_e32 v160, 16, v226
	v_add_f32_e32 v158, 1.0, v158
	v_add_f32_e32 v159, 1.0, v159
	v_rcp_f32_e32 v158, v158
	v_rcp_f32_e32 v159, v159
	v_and_b32_e32 v161, 0xffff0000, v226
	v_pk_mul_f32 v[160:161], v[220:221], v[160:161] op_sel_hi:[0,1]
	v_cvt_pk_bf16_f32 v155, v0, v1
	v_pk_mul_f32 v[138:139], v[138:139], v[158:159]
	v_mul_f32_e32 v158, 0xbfb8aa3b, v140
	v_exp_f32_e32 v198, v158
	v_mul_f32_e32 v158, 0xbfb8aa3b, v141
	v_exp_f32_e32 v199, v158
	s_waitcnt vmcnt(0)
	v_pk_mul_f32 v[160:161], v[114:115], v[160:161]
	v_lshl_add_u64 v[0:1], s[4:5], 0, v[218:219]
	v_pk_mul_f32 v[158:159], v[138:139], v[160:161]
	v_add_f32_e32 v138, 1.0, v198
	v_add_f32_e32 v139, 1.0, v199
	v_rcp_f32_e32 v138, v138
	v_rcp_f32_e32 v139, v139
	v_lshl_add_u64 v[0:1], v[0:1], 0, v[202:203]
	global_store_dwordx4 v[0:1], v[154:157], off
	v_pk_mul_f32 v[138:139], v[140:141], v[138:139]
	s_nop 0
	v_lshlrev_b32_e32 v154, 16, v227
	v_and_b32_e32 v155, 0xffff0000, v227
	v_pk_mul_f32 v[154:155], v[220:221], v[154:155] op_sel_hi:[0,1]
	v_pk_mul_f32 v[154:155], v[116:117], v[154:155]
	v_cvt_pk_bf16_f32 v140, v158, v159
	v_pk_mul_f32 v[154:155], v[138:139], v[154:155]
	v_cvt_pk_bf16_f32 v138, v146, v147
	v_mul_f32_e32 v146, 0xbfb8aa3b, v134
	v_mul_f32_e32 v147, 0xbfb8aa3b, v135
	v_exp_f32_e32 v146, v146
	v_exp_f32_e32 v147, v147
	v_cvt_pk_bf16_f32 v139, v148, v149
	v_cvt_pk_bf16_f32 v141, v154, v155
	global_store_dwordx4 v[0:1], v[138:141], off offset:256
	v_add_f32_e32 v0, 1.0, v146
	v_add_f32_e32 v1, 1.0, v147
	v_rcp_f32_e32 v0, v0
	v_rcp_f32_e32 v1, v1
	v_lshlrev_b32_e32 v138, 16, v228
	v_and_b32_e32 v139, 0xffff0000, v228
	v_mov_b32_e32 v140, v221
	v_pk_mul_f32 v[0:1], v[134:135], v[0:1]
	v_mul_f32_e32 v134, 0xbfb8aa3b, v136
	v_mul_f32_e32 v135, 0xbfb8aa3b, v137
	v_exp_f32_e32 v134, v134
	v_exp_f32_e32 v135, v135
	v_pk_mul_f32 v[138:139], v[140:141], v[138:139] op_sel_hi:[0,1]
	v_pk_mul_f32 v[138:139], v[106:107], v[138:139]
	v_add_f32_e32 v134, 1.0, v134
	v_add_f32_e32 v135, 1.0, v135
	v_rcp_f32_e32 v134, v134
	v_rcp_f32_e32 v135, v135
	v_pk_mul_f32 v[0:1], v[0:1], v[138:139]
	v_lshlrev_b32_e32 v138, 16, v229
	v_and_b32_e32 v139, 0xffff0000, v229
	v_pk_mul_f32 v[134:135], v[136:137], v[134:135]
	v_mul_f32_e32 v136, 0xbfb8aa3b, v130
	v_mul_f32_e32 v137, 0xbfb8aa3b, v131
	v_exp_f32_e32 v136, v136
	v_exp_f32_e32 v137, v137
	v_pk_mul_f32 v[138:139], v[140:141], v[138:139] op_sel_hi:[0,1]
	v_pk_mul_f32 v[138:139], v[108:109], v[138:139]
	v_add_f32_e32 v136, 1.0, v136
	v_add_f32_e32 v137, 1.0, v137
	v_rcp_f32_e32 v136, v136
	v_rcp_f32_e32 v137, v137
	v_pk_mul_f32 v[134:135], v[134:135], v[138:139]
	v_lshlrev_b32_e32 v138, 16, v230
	v_and_b32_e32 v139, 0xffff0000, v230
	v_pk_mul_f32 v[130:131], v[130:131], v[136:137]
	v_mul_f32_e32 v136, 0xbfb8aa3b, v132
	v_pk_mul_f32 v[138:139], v[140:141], v[138:139] op_sel_hi:[0,1]
	v_exp_f32_e32 v141, v136
	v_mul_f32_e32 v136, 0xbfb8aa3b, v133
	v_exp_f32_e32 v146, v136
	v_pk_mul_f32 v[138:139], v[98:99], v[138:139]
	s_nop 0
	v_pk_mul_f32 v[136:137], v[130:131], v[138:139]
	v_add_f32_e32 v130, 1.0, v141
	v_add_f32_e32 v131, 1.0, v146
	v_rcp_f32_e32 v130, v130
	v_rcp_f32_e32 v131, v131
	v_lshlrev_b32_e32 v138, 16, v231
	v_and_b32_e32 v139, 0xffff0000, v231
	v_pk_mul_f32 v[138:139], v[140:141], v[138:139] op_sel_hi:[0,1]
	v_pk_mul_f32 v[138:139], v[100:101], v[138:139]
	v_pk_mul_f32 v[130:131], v[132:133], v[130:131]
	v_cvt_pk_bf16_f32 v132, v136, v137
	v_pk_mul_f32 v[138:139], v[130:131], v[138:139]
	v_cvt_pk_bf16_f32 v131, v134, v135
	v_mul_f32_e32 v134, 0xbfb8aa3b, v122
	v_mul_f32_e32 v135, 0xbfb8aa3b, v123
	v_exp_f32_e32 v134, v134
	v_exp_f32_e32 v135, v135
	v_cvt_pk_bf16_f32 v130, v0, v1
	v_lshl_add_u64 v[0:1], s[4:5], 0, v[216:217]
	v_cvt_pk_bf16_f32 v133, v138, v139
	v_lshl_add_u64 v[0:1], v[0:1], 0, v[202:203]
	global_store_dwordx4 v[0:1], v[130:133], off
	s_nop 1
	v_add_f32_e32 v130, 1.0, v134
	v_add_f32_e32 v131, 1.0, v135
	v_rcp_f32_e32 v130, v130
	v_rcp_f32_e32 v131, v131
	v_lshlrev_b32_e32 v132, 16, v194
	v_and_b32_e32 v133, 0xffff0000, v194
	v_pk_mul_f32 v[132:133], v[140:141], v[132:133] op_sel_hi:[0,1]
	v_pk_mul_f32 v[122:123], v[122:123], v[130:131]
	v_mul_f32_e32 v130, 0xbfb8aa3b, v124
	v_mul_f32_e32 v131, 0xbfb8aa3b, v125
	v_exp_f32_e32 v130, v130
	v_exp_f32_e32 v131, v131
	v_pk_mul_f32 v[132:133], v[118:119], v[132:133]
	v_add_f32_e32 v130, 1.0, v130
	v_add_f32_e32 v131, 1.0, v131
	v_rcp_f32_e32 v130, v130
	v_rcp_f32_e32 v131, v131
	v_pk_mul_f32 v[122:123], v[122:123], v[132:133]
	v_lshlrev_b32_e32 v132, 16, v195
	v_and_b32_e32 v133, 0xffff0000, v195
	v_pk_mul_f32 v[124:125], v[124:125], v[130:131]
	v_mul_f32_e32 v130, 0xbfb8aa3b, v102
	v_mul_f32_e32 v131, 0xbfb8aa3b, v103
	v_exp_f32_e32 v130, v130
	v_exp_f32_e32 v131, v131
	v_pk_mul_f32 v[132:133], v[140:141], v[132:133] op_sel_hi:[0,1]
	v_pk_mul_f32 v[132:133], v[120:121], v[132:133]
	v_add_f32_e32 v130, 1.0, v130
	v_add_f32_e32 v131, 1.0, v131
	v_rcp_f32_e32 v130, v130
	v_rcp_f32_e32 v131, v131
	v_pk_mul_f32 v[124:125], v[124:125], v[132:133]
	v_lshlrev_b32_e32 v132, 16, v196
	v_and_b32_e32 v133, 0xffff0000, v196
	v_pk_mul_f32 v[102:103], v[102:103], v[130:131]
	v_mul_f32_e32 v130, 0xbfb8aa3b, v104
	v_exp_f32_e32 v134, v130
	v_mul_f32_e32 v130, 0xbfb8aa3b, v105
	v_exp_f32_e32 v135, v130
	v_pk_mul_f32 v[132:133], v[140:141], v[132:133] op_sel_hi:[0,1]
	v_pk_mul_f32 v[132:133], v[114:115], v[132:133]
	s_nop 0
	v_pk_mul_f32 v[130:131], v[102:103], v[132:133]
	v_add_f32_e32 v102, 1.0, v134
	v_add_f32_e32 v103, 1.0, v135
	v_rcp_f32_e32 v102, v102
	v_rcp_f32_e32 v103, v103
	v_lshlrev_b32_e32 v132, 16, v197
	v_and_b32_e32 v133, 0xffff0000, v197
	v_pk_mul_f32 v[132:133], v[140:141], v[132:133] op_sel_hi:[0,1]
	v_pk_mul_f32 v[132:133], v[116:117], v[132:133]
	v_pk_mul_f32 v[102:103], v[104:105], v[102:103]
	v_cvt_pk_bf16_f32 v104, v130, v131
	v_pk_mul_f32 v[132:133], v[102:103], v[132:133]
	v_cvt_pk_bf16_f32 v102, v122, v123
	v_cvt_pk_bf16_f32 v103, v124, v125
	v_cvt_pk_bf16_f32 v105, v132, v133
	global_store_dwordx4 v[0:1], v[102:105], off offset:256
	v_mul_f32_e32 v0, 0xbfb8aa3b, v94
	s_nop 0
	v_exp_f32_e32 v102, v0
	v_mul_f32_e32 v0, 0xbfb8aa3b, v95
	v_exp_f32_e32 v103, v0
	ds_read2_b32 v[0:1], v222 offset0:32 offset1:48
	v_add_f32_e32 v102, 1.0, v102
	v_rcp_f32_e32 v102, v102
	v_add_f32_e32 v103, 1.0, v103
	v_rcp_f32_e32 v103, v103
	v_lshlrev_b32_e32 v104, 16, v190
	v_and_b32_e32 v105, 0xffff0000, v190
	s_waitcnt lgkmcnt(0)
	v_pk_mul_f32 v[104:105], v[0:1], v[104:105] op_sel_hi:[0,1]
	v_pk_mul_f32 v[94:95], v[94:95], v[102:103]
	v_mul_f32_e32 v102, 0xbfb8aa3b, v96
	v_mul_f32_e32 v103, 0xbfb8aa3b, v97
	v_exp_f32_e32 v102, v102
	v_exp_f32_e32 v103, v103
	v_pk_mul_f32 v[104:105], v[106:107], v[104:105]
	v_add_f32_e32 v102, 1.0, v102
	v_add_f32_e32 v103, 1.0, v103
	v_rcp_f32_e32 v102, v102
	v_rcp_f32_e32 v103, v103
	v_pk_mul_f32 v[94:95], v[94:95], v[104:105]
	v_lshlrev_b32_e32 v104, 16, v191
	v_and_b32_e32 v105, 0xffff0000, v191
	v_pk_mul_f32 v[96:97], v[96:97], v[102:103]
	v_mul_f32_e32 v102, 0xbfb8aa3b, v90
	v_mul_f32_e32 v103, 0xbfb8aa3b, v91
	v_exp_f32_e32 v102, v102
	v_exp_f32_e32 v103, v103
	v_pk_mul_f32 v[104:105], v[0:1], v[104:105] op_sel_hi:[0,1]
	v_pk_mul_f32 v[104:105], v[108:109], v[104:105]
	v_add_f32_e32 v102, 1.0, v102
	v_add_f32_e32 v103, 1.0, v103
	v_rcp_f32_e32 v102, v102
	v_rcp_f32_e32 v103, v103
	v_pk_mul_f32 v[96:97], v[96:97], v[104:105]
	v_lshlrev_b32_e32 v104, 16, v192
	v_and_b32_e32 v105, 0xffff0000, v192
	v_pk_mul_f32 v[90:91], v[90:91], v[102:103]
	v_mul_f32_e32 v102, 0xbfb8aa3b, v92
	v_exp_f32_e32 v122, v102
	v_mul_f32_e32 v102, 0xbfb8aa3b, v93
	v_exp_f32_e32 v123, v102
	v_pk_mul_f32 v[104:105], v[0:1], v[104:105] op_sel_hi:[0,1]
	v_pk_mul_f32 v[104:105], v[98:99], v[104:105]
	s_nop 0
	v_pk_mul_f32 v[102:103], v[90:91], v[104:105]
	v_add_f32_e32 v90, 1.0, v122
	v_add_f32_e32 v91, 1.0, v123
	v_rcp_f32_e32 v90, v90
	v_rcp_f32_e32 v91, v91
	v_lshlrev_b32_e32 v104, 16, v193
	v_and_b32_e32 v105, 0xffff0000, v193
	v_pk_mul_f32 v[104:105], v[0:1], v[104:105] op_sel_hi:[0,1]
	v_pk_mul_f32 v[104:105], v[100:101], v[104:105]
	v_pk_mul_f32 v[90:91], v[92:93], v[90:91]
	v_cvt_pk_bf16_f32 v92, v102, v103
	v_pk_mul_f32 v[104:105], v[90:91], v[104:105]
	v_cvt_pk_bf16_f32 v91, v96, v97
	v_mul_f32_e32 v96, 0xbfb8aa3b, v86
	v_mul_f32_e32 v97, 0xbfb8aa3b, v87
	v_exp_f32_e32 v96, v96
	v_exp_f32_e32 v97, v97
	v_cvt_pk_bf16_f32 v90, v94, v95
	v_lshl_add_u64 v[94:95], s[4:5], 0, v[214:215]
	v_cvt_pk_bf16_f32 v93, v104, v105
	v_lshl_add_u64 v[94:95], v[94:95], 0, v[202:203]
	global_store_dwordx4 v[94:95], v[90:93], off
	s_nop 1
	v_add_f32_e32 v90, 1.0, v96
	v_add_f32_e32 v91, 1.0, v97
	v_rcp_f32_e32 v90, v90
	v_rcp_f32_e32 v91, v91
	v_lshlrev_b32_e32 v92, 16, v186
	v_and_b32_e32 v93, 0xffff0000, v186
	v_pk_mul_f32 v[92:93], v[0:1], v[92:93] op_sel_hi:[0,1]
	v_pk_mul_f32 v[86:87], v[86:87], v[90:91]
	v_mul_f32_e32 v90, 0xbfb8aa3b, v88
	v_mul_f32_e32 v91, 0xbfb8aa3b, v89
	v_exp_f32_e32 v90, v90
	v_exp_f32_e32 v91, v91
	v_pk_mul_f32 v[92:93], v[118:119], v[92:93]
	v_add_f32_e32 v90, 1.0, v90
	v_add_f32_e32 v91, 1.0, v91
	v_rcp_f32_e32 v90, v90
	v_rcp_f32_e32 v91, v91
	v_pk_mul_f32 v[86:87], v[86:87], v[92:93]
	v_lshlrev_b32_e32 v92, 16, v187
	v_and_b32_e32 v93, 0xffff0000, v187
	v_pk_mul_f32 v[88:89], v[88:89], v[90:91]
	v_mul_f32_e32 v90, 0xbfb8aa3b, v82
	v_mul_f32_e32 v91, 0xbfb8aa3b, v83
	v_exp_f32_e32 v90, v90
	v_exp_f32_e32 v91, v91
	v_pk_mul_f32 v[92:93], v[0:1], v[92:93] op_sel_hi:[0,1]
	v_pk_mul_f32 v[92:93], v[120:121], v[92:93]
	v_add_f32_e32 v90, 1.0, v90
	v_add_f32_e32 v91, 1.0, v91
	v_rcp_f32_e32 v90, v90
	v_rcp_f32_e32 v91, v91
	v_pk_mul_f32 v[88:89], v[88:89], v[92:93]
	v_lshlrev_b32_e32 v92, 16, v188
	v_and_b32_e32 v93, 0xffff0000, v188
	v_pk_mul_f32 v[82:83], v[82:83], v[90:91]
	v_mul_f32_e32 v90, 0xbfb8aa3b, v84
	v_exp_f32_e32 v96, v90
	v_mul_f32_e32 v90, 0xbfb8aa3b, v85
	v_exp_f32_e32 v97, v90
	v_pk_mul_f32 v[92:93], v[0:1], v[92:93] op_sel_hi:[0,1]
	v_pk_mul_f32 v[92:93], v[114:115], v[92:93]
	s_nop 0
	v_pk_mul_f32 v[90:91], v[82:83], v[92:93]
	v_add_f32_e32 v82, 1.0, v96
	v_add_f32_e32 v83, 1.0, v97
	v_rcp_f32_e32 v82, v82
	v_rcp_f32_e32 v83, v83
	v_lshlrev_b32_e32 v92, 16, v189
	v_and_b32_e32 v93, 0xffff0000, v189
	v_pk_mul_f32 v[92:93], v[0:1], v[92:93] op_sel_hi:[0,1]
	v_pk_mul_f32 v[92:93], v[116:117], v[92:93]
	v_pk_mul_f32 v[82:83], v[84:85], v[82:83]
	v_mul_f32_e32 v0, 0xbfb8aa3b, v78
	v_pk_mul_f32 v[92:93], v[82:83], v[92:93]
	v_cvt_pk_bf16_f32 v82, v86, v87
	v_exp_f32_e32 v0, v0
	v_mul_f32_e32 v86, 0xbfb8aa3b, v79
	v_exp_f32_e32 v86, v86
	v_cvt_pk_bf16_f32 v83, v88, v89
	v_cvt_pk_bf16_f32 v84, v90, v91
	v_cvt_pk_bf16_f32 v85, v92, v93
	v_add_f32_e32 v0, 1.0, v0
	global_store_dwordx4 v[94:95], v[82:85], off offset:256
	s_nop 1
	v_rcp_f32_e32 v82, v0
	v_add_f32_e32 v0, 1.0, v86
	v_rcp_f32_e32 v83, v0
	v_lshlrev_b32_e32 v84, 16, v182
	v_and_b32_e32 v85, 0xffff0000, v182
	v_mov_b32_e32 v0, v1
	v_pk_mul_f32 v[84:85], v[0:1], v[84:85] op_sel_hi:[0,1]
	v_mul_f32_e32 v1, 0xbfb8aa3b, v80
	v_pk_mul_f32 v[78:79], v[78:79], v[82:83]
	v_exp_f32_e32 v1, v1
	v_mul_f32_e32 v82, 0xbfb8aa3b, v81
	v_exp_f32_e32 v83, v82
	v_pk_mul_f32 v[84:85], v[106:107], v[84:85]
	v_add_f32_e32 v1, 1.0, v1
	v_rcp_f32_e32 v82, v1
	v_add_f32_e32 v1, 1.0, v83
	v_rcp_f32_e32 v83, v1
	v_pk_mul_f32 v[78:79], v[78:79], v[84:85]
	v_lshlrev_b32_e32 v84, 16, v183
	v_and_b32_e32 v85, 0xffff0000, v183
	v_pk_mul_f32 v[84:85], v[0:1], v[84:85] op_sel_hi:[0,1]
	v_mul_f32_e32 v1, 0xbfb8aa3b, v74
	v_pk_mul_f32 v[80:81], v[80:81], v[82:83]
	v_exp_f32_e32 v1, v1
	v_mul_f32_e32 v82, 0xbfb8aa3b, v75
	v_exp_f32_e32 v83, v82
	v_pk_mul_f32 v[84:85], v[108:109], v[84:85]
	v_add_f32_e32 v1, 1.0, v1
	v_rcp_f32_e32 v82, v1
	v_add_f32_e32 v1, 1.0, v83
	v_rcp_f32_e32 v83, v1
	v_pk_mul_f32 v[80:81], v[80:81], v[84:85]
	v_lshlrev_b32_e32 v84, 16, v184
	v_and_b32_e32 v85, 0xffff0000, v184
	v_pk_mul_f32 v[84:85], v[0:1], v[84:85] op_sel_hi:[0,1]
	v_mul_f32_e32 v1, 0xbfb8aa3b, v76
	v_pk_mul_f32 v[74:75], v[74:75], v[82:83]
	v_exp_f32_e32 v1, v1
	v_mul_f32_e32 v82, 0xbfb8aa3b, v77
	v_exp_f32_e32 v86, v82
	v_pk_mul_f32 v[84:85], v[98:99], v[84:85]
	v_add_f32_e32 v1, 1.0, v1
	v_pk_mul_f32 v[82:83], v[74:75], v[84:85]
	v_rcp_f32_e32 v74, v1
	v_add_f32_e32 v1, 1.0, v86
	v_rcp_f32_e32 v75, v1
	v_lshlrev_b32_e32 v84, 16, v185
	v_and_b32_e32 v85, 0xffff0000, v185
	v_pk_mul_f32 v[84:85], v[0:1], v[84:85] op_sel_hi:[0,1]
	v_pk_mul_f32 v[84:85], v[100:101], v[84:85]
	v_pk_mul_f32 v[74:75], v[76:77], v[74:75]
	v_mul_f32_e32 v1, 0xbfb8aa3b, v70
	v_pk_mul_f32 v[84:85], v[74:75], v[84:85]
	v_cvt_pk_bf16_f32 v75, v80, v81
	v_exp_f32_e32 v1, v1
	v_mul_f32_e32 v80, 0xbfb8aa3b, v71
	v_exp_f32_e32 v80, v80
	v_cvt_pk_bf16_f32 v74, v78, v79
	v_lshl_add_u64 v[78:79], s[4:5], 0, v[212:213]
	v_cvt_pk_bf16_f32 v76, v82, v83
	v_cvt_pk_bf16_f32 v77, v84, v85
	v_lshl_add_u64 v[78:79], v[78:79], 0, v[202:203]
	v_add_f32_e32 v1, 1.0, v1
	global_store_dwordx4 v[78:79], v[74:77], off
	s_nop 1
	v_rcp_f32_e32 v74, v1
	v_add_f32_e32 v1, 1.0, v80
	v_rcp_f32_e32 v75, v1
	v_lshlrev_b32_e32 v76, 16, v178
	v_and_b32_e32 v77, 0xffff0000, v178
	v_pk_mul_f32 v[76:77], v[0:1], v[76:77] op_sel_hi:[0,1]
	v_mul_f32_e32 v1, 0xbfb8aa3b, v72
	v_pk_mul_f32 v[70:71], v[70:71], v[74:75]
	v_exp_f32_e32 v1, v1
	v_mul_f32_e32 v74, 0xbfb8aa3b, v73
	v_exp_f32_e32 v75, v74
	v_pk_mul_f32 v[76:77], v[118:119], v[76:77]
	v_add_f32_e32 v1, 1.0, v1
	v_rcp_f32_e32 v74, v1
	v_add_f32_e32 v1, 1.0, v75
	v_rcp_f32_e32 v75, v1
	v_pk_mul_f32 v[70:71], v[70:71], v[76:77]
	v_lshlrev_b32_e32 v76, 16, v179
	v_and_b32_e32 v77, 0xffff0000, v179
	v_pk_mul_f32 v[76:77], v[0:1], v[76:77] op_sel_hi:[0,1]
	v_mul_f32_e32 v1, 0xbfb8aa3b, v66
	v_pk_mul_f32 v[72:73], v[72:73], v[74:75]
	v_exp_f32_e32 v1, v1
	v_mul_f32_e32 v74, 0xbfb8aa3b, v67
	v_exp_f32_e32 v75, v74
	v_pk_mul_f32 v[76:77], v[120:121], v[76:77]
	v_add_f32_e32 v1, 1.0, v1
	v_rcp_f32_e32 v74, v1
	v_add_f32_e32 v1, 1.0, v75
	v_rcp_f32_e32 v75, v1
	v_pk_mul_f32 v[72:73], v[72:73], v[76:77]
	v_lshlrev_b32_e32 v76, 16, v180
	v_and_b32_e32 v77, 0xffff0000, v180
	v_pk_mul_f32 v[76:77], v[0:1], v[76:77] op_sel_hi:[0,1]
	v_mul_f32_e32 v1, 0xbfb8aa3b, v68
	v_pk_mul_f32 v[66:67], v[66:67], v[74:75]
	v_exp_f32_e32 v1, v1
	v_mul_f32_e32 v74, 0xbfb8aa3b, v69
	v_exp_f32_e32 v80, v74
	v_pk_mul_f32 v[76:77], v[114:115], v[76:77]
	v_add_f32_e32 v1, 1.0, v1
	v_pk_mul_f32 v[74:75], v[66:67], v[76:77]
	v_rcp_f32_e32 v66, v1
	v_add_f32_e32 v1, 1.0, v80
	v_rcp_f32_e32 v67, v1
	v_lshlrev_b32_e32 v76, 16, v181
	v_and_b32_e32 v77, 0xffff0000, v181
	v_pk_mul_f32 v[0:1], v[0:1], v[76:77] op_sel_hi:[0,1]
	v_pk_mul_f32 v[0:1], v[116:117], v[0:1]
	v_pk_mul_f32 v[66:67], v[68:69], v[66:67]
	v_cvt_pk_bf16_f32 v68, v74, v75
	v_pk_mul_f32 v[0:1], v[66:67], v[0:1]
	v_cvt_pk_bf16_f32 v66, v70, v71
	v_cvt_pk_bf16_f32 v67, v72, v73
	v_cvt_pk_bf16_f32 v69, v0, v1
	v_mul_f32_e32 v0, 0xbfb8aa3b, v62
	global_store_dwordx4 v[78:79], v[66:69], off offset:256
	s_nop 1
	v_exp_f32_e32 v66, v0
	v_mul_f32_e32 v0, 0xbfb8aa3b, v63
	v_exp_f32_e32 v67, v0
	ds_read2_b32 v[0:1], v222 offset0:128 offset1:144
	v_add_f32_e32 v66, 1.0, v66
	v_rcp_f32_e32 v66, v66
	v_add_f32_e32 v67, 1.0, v67
	v_rcp_f32_e32 v67, v67
	v_lshlrev_b32_e32 v68, 16, v174
	v_and_b32_e32 v69, 0xffff0000, v174
	s_waitcnt lgkmcnt(0)
	v_pk_mul_f32 v[68:69], v[0:1], v[68:69] op_sel_hi:[0,1]
	v_pk_mul_f32 v[62:63], v[62:63], v[66:67]
	v_mul_f32_e32 v66, 0xbfb8aa3b, v64
	v_mul_f32_e32 v67, 0xbfb8aa3b, v65
	v_exp_f32_e32 v66, v66
	v_exp_f32_e32 v67, v67
	v_pk_mul_f32 v[68:69], v[106:107], v[68:69]
	v_add_f32_e32 v66, 1.0, v66
	v_add_f32_e32 v67, 1.0, v67
	v_rcp_f32_e32 v66, v66
	v_rcp_f32_e32 v67, v67
	v_pk_mul_f32 v[62:63], v[62:63], v[68:69]
	v_lshlrev_b32_e32 v68, 16, v175
	v_and_b32_e32 v69, 0xffff0000, v175
	v_pk_mul_f32 v[64:65], v[64:65], v[66:67]
	v_mul_f32_e32 v66, 0xbfb8aa3b, v58
	v_mul_f32_e32 v67, 0xbfb8aa3b, v59
	v_exp_f32_e32 v66, v66
	v_exp_f32_e32 v67, v67
	v_pk_mul_f32 v[68:69], v[0:1], v[68:69] op_sel_hi:[0,1]
	v_pk_mul_f32 v[68:69], v[108:109], v[68:69]
	v_add_f32_e32 v66, 1.0, v66
	v_add_f32_e32 v67, 1.0, v67
	v_rcp_f32_e32 v66, v66
	v_rcp_f32_e32 v67, v67
	v_pk_mul_f32 v[64:65], v[64:65], v[68:69]
	v_lshlrev_b32_e32 v68, 16, v176
	v_and_b32_e32 v69, 0xffff0000, v176
	v_pk_mul_f32 v[58:59], v[58:59], v[66:67]
	v_mul_f32_e32 v66, 0xbfb8aa3b, v60
	v_exp_f32_e32 v70, v66
	v_mul_f32_e32 v66, 0xbfb8aa3b, v61
	v_exp_f32_e32 v71, v66
	v_pk_mul_f32 v[68:69], v[0:1], v[68:69] op_sel_hi:[0,1]
	v_pk_mul_f32 v[68:69], v[98:99], v[68:69]
	s_nop 0
	v_pk_mul_f32 v[66:67], v[58:59], v[68:69]
	v_add_f32_e32 v58, 1.0, v70
	v_add_f32_e32 v59, 1.0, v71
	v_rcp_f32_e32 v58, v58
	v_rcp_f32_e32 v59, v59
	v_lshlrev_b32_e32 v68, 16, v177
	v_and_b32_e32 v69, 0xffff0000, v177
	v_pk_mul_f32 v[68:69], v[0:1], v[68:69] op_sel_hi:[0,1]
	v_pk_mul_f32 v[68:69], v[100:101], v[68:69]
	v_pk_mul_f32 v[58:59], v[60:61], v[58:59]
	v_cvt_pk_bf16_f32 v60, v66, v67
	v_pk_mul_f32 v[68:69], v[58:59], v[68:69]
	v_cvt_pk_bf16_f32 v59, v64, v65
	v_mul_f32_e32 v64, 0xbfb8aa3b, v54
	v_mul_f32_e32 v65, 0xbfb8aa3b, v55
	v_exp_f32_e32 v64, v64
	v_exp_f32_e32 v65, v65
	v_cvt_pk_bf16_f32 v58, v62, v63
	v_lshl_add_u64 v[62:63], s[4:5], 0, v[210:211]
	v_cvt_pk_bf16_f32 v61, v68, v69
	v_lshl_add_u64 v[62:63], v[62:63], 0, v[202:203]
	global_store_dwordx4 v[62:63], v[58:61], off
	s_nop 1
	v_add_f32_e32 v58, 1.0, v64
	v_add_f32_e32 v59, 1.0, v65
	v_rcp_f32_e32 v58, v58
	v_rcp_f32_e32 v59, v59
	v_lshlrev_b32_e32 v60, 16, v170
	v_and_b32_e32 v61, 0xffff0000, v170
	v_pk_mul_f32 v[60:61], v[0:1], v[60:61] op_sel_hi:[0,1]
	v_pk_mul_f32 v[54:55], v[54:55], v[58:59]
	v_mul_f32_e32 v58, 0xbfb8aa3b, v56
	v_mul_f32_e32 v59, 0xbfb8aa3b, v57
	v_exp_f32_e32 v58, v58
	v_exp_f32_e32 v59, v59
	v_pk_mul_f32 v[60:61], v[118:119], v[60:61]
	v_add_f32_e32 v58, 1.0, v58
	v_add_f32_e32 v59, 1.0, v59
	v_rcp_f32_e32 v58, v58
	v_rcp_f32_e32 v59, v59
	v_pk_mul_f32 v[54:55], v[54:55], v[60:61]
	v_lshlrev_b32_e32 v60, 16, v171
	v_and_b32_e32 v61, 0xffff0000, v171
	v_pk_mul_f32 v[56:57], v[56:57], v[58:59]
	v_mul_f32_e32 v58, 0xbfb8aa3b, v50
	v_mul_f32_e32 v59, 0xbfb8aa3b, v51
	v_exp_f32_e32 v58, v58
	v_exp_f32_e32 v59, v59
	v_pk_mul_f32 v[60:61], v[0:1], v[60:61] op_sel_hi:[0,1]
	v_pk_mul_f32 v[60:61], v[120:121], v[60:61]
	v_add_f32_e32 v58, 1.0, v58
	v_add_f32_e32 v59, 1.0, v59
	v_rcp_f32_e32 v58, v58
	v_rcp_f32_e32 v59, v59
	v_pk_mul_f32 v[56:57], v[56:57], v[60:61]
	v_lshlrev_b32_e32 v60, 16, v172
	v_and_b32_e32 v61, 0xffff0000, v172
	v_pk_mul_f32 v[50:51], v[50:51], v[58:59]
	v_mul_f32_e32 v58, 0xbfb8aa3b, v52
	v_exp_f32_e32 v64, v58
	v_mul_f32_e32 v58, 0xbfb8aa3b, v53
	v_exp_f32_e32 v65, v58
	v_pk_mul_f32 v[60:61], v[0:1], v[60:61] op_sel_hi:[0,1]
	v_pk_mul_f32 v[60:61], v[114:115], v[60:61]
	s_nop 0
	v_pk_mul_f32 v[58:59], v[50:51], v[60:61]
	v_add_f32_e32 v50, 1.0, v64
	v_add_f32_e32 v51, 1.0, v65
	v_rcp_f32_e32 v50, v50
	v_rcp_f32_e32 v51, v51
	v_lshlrev_b32_e32 v60, 16, v173
	v_and_b32_e32 v61, 0xffff0000, v173
	v_pk_mul_f32 v[60:61], v[0:1], v[60:61] op_sel_hi:[0,1]
	v_pk_mul_f32 v[60:61], v[116:117], v[60:61]
	v_pk_mul_f32 v[50:51], v[52:53], v[50:51]
	v_mul_f32_e32 v0, 0xbfb8aa3b, v46
	v_pk_mul_f32 v[60:61], v[50:51], v[60:61]
	v_cvt_pk_bf16_f32 v50, v54, v55
	v_exp_f32_e32 v0, v0
	v_mul_f32_e32 v54, 0xbfb8aa3b, v47
	v_exp_f32_e32 v54, v54
	v_cvt_pk_bf16_f32 v51, v56, v57
	v_cvt_pk_bf16_f32 v52, v58, v59
	v_cvt_pk_bf16_f32 v53, v60, v61
	v_add_f32_e32 v0, 1.0, v0
	global_store_dwordx4 v[62:63], v[50:53], off offset:256
	s_nop 1
	v_rcp_f32_e32 v50, v0
	v_add_f32_e32 v0, 1.0, v54
	v_rcp_f32_e32 v51, v0
	v_lshlrev_b32_e32 v52, 16, v166
	v_and_b32_e32 v53, 0xffff0000, v166
	v_mov_b32_e32 v0, v1
	v_pk_mul_f32 v[52:53], v[0:1], v[52:53] op_sel_hi:[0,1]
	v_mul_f32_e32 v1, 0xbfb8aa3b, v48
	v_pk_mul_f32 v[46:47], v[46:47], v[50:51]
	v_exp_f32_e32 v1, v1
	v_mul_f32_e32 v50, 0xbfb8aa3b, v49
	v_exp_f32_e32 v51, v50
	v_pk_mul_f32 v[52:53], v[106:107], v[52:53]
	v_add_f32_e32 v1, 1.0, v1
	v_rcp_f32_e32 v50, v1
	v_add_f32_e32 v1, 1.0, v51
	v_rcp_f32_e32 v51, v1
	v_pk_mul_f32 v[46:47], v[46:47], v[52:53]
	v_lshlrev_b32_e32 v52, 16, v167
	v_and_b32_e32 v53, 0xffff0000, v167
	v_pk_mul_f32 v[52:53], v[0:1], v[52:53] op_sel_hi:[0,1]
	v_mul_f32_e32 v1, 0xbfb8aa3b, v42
	v_pk_mul_f32 v[48:49], v[48:49], v[50:51]
	v_exp_f32_e32 v1, v1
	v_mul_f32_e32 v50, 0xbfb8aa3b, v43
	v_exp_f32_e32 v51, v50
	v_pk_mul_f32 v[52:53], v[108:109], v[52:53]
	v_add_f32_e32 v1, 1.0, v1
	v_rcp_f32_e32 v50, v1
	v_add_f32_e32 v1, 1.0, v51
	v_rcp_f32_e32 v51, v1
	v_pk_mul_f32 v[48:49], v[48:49], v[52:53]
	v_lshlrev_b32_e32 v52, 16, v168
	v_and_b32_e32 v53, 0xffff0000, v168
	v_pk_mul_f32 v[52:53], v[0:1], v[52:53] op_sel_hi:[0,1]
	v_mul_f32_e32 v1, 0xbfb8aa3b, v44
	v_pk_mul_f32 v[42:43], v[42:43], v[50:51]
	v_exp_f32_e32 v1, v1
	v_mul_f32_e32 v50, 0xbfb8aa3b, v45
	v_exp_f32_e32 v54, v50
	v_pk_mul_f32 v[52:53], v[98:99], v[52:53]
	v_add_f32_e32 v1, 1.0, v1
	v_pk_mul_f32 v[50:51], v[42:43], v[52:53]
	v_rcp_f32_e32 v42, v1
	v_add_f32_e32 v1, 1.0, v54
	v_rcp_f32_e32 v43, v1
	v_lshlrev_b32_e32 v52, 16, v169
	v_and_b32_e32 v53, 0xffff0000, v169
	v_pk_mul_f32 v[52:53], v[0:1], v[52:53] op_sel_hi:[0,1]
	v_pk_mul_f32 v[52:53], v[100:101], v[52:53]
	v_pk_mul_f32 v[42:43], v[44:45], v[42:43]
	v_mul_f32_e32 v1, 0xbfb8aa3b, v38
	v_pk_mul_f32 v[52:53], v[42:43], v[52:53]
	v_cvt_pk_bf16_f32 v43, v48, v49
	v_exp_f32_e32 v1, v1
	v_mul_f32_e32 v48, 0xbfb8aa3b, v39
	v_exp_f32_e32 v48, v48
	v_cvt_pk_bf16_f32 v42, v46, v47
	v_lshl_add_u64 v[46:47], s[4:5], 0, v[208:209]
	v_cvt_pk_bf16_f32 v44, v50, v51
	v_cvt_pk_bf16_f32 v45, v52, v53
	v_lshl_add_u64 v[46:47], v[46:47], 0, v[202:203]
	v_add_f32_e32 v1, 1.0, v1
	global_store_dwordx4 v[46:47], v[42:45], off
	s_nop 1
	v_rcp_f32_e32 v42, v1
	v_add_f32_e32 v1, 1.0, v48
	v_rcp_f32_e32 v43, v1
	v_lshlrev_b32_e32 v44, 16, v162
	v_and_b32_e32 v45, 0xffff0000, v162
	v_pk_mul_f32 v[44:45], v[0:1], v[44:45] op_sel_hi:[0,1]
	v_mul_f32_e32 v1, 0xbfb8aa3b, v40
	v_pk_mul_f32 v[38:39], v[38:39], v[42:43]
	v_exp_f32_e32 v1, v1
	v_mul_f32_e32 v42, 0xbfb8aa3b, v41
	v_exp_f32_e32 v43, v42
	v_pk_mul_f32 v[44:45], v[118:119], v[44:45]
	v_add_f32_e32 v1, 1.0, v1
	v_rcp_f32_e32 v42, v1
	v_add_f32_e32 v1, 1.0, v43
	v_rcp_f32_e32 v43, v1
	v_pk_mul_f32 v[38:39], v[38:39], v[44:45]
	v_lshlrev_b32_e32 v44, 16, v163
	v_and_b32_e32 v45, 0xffff0000, v163
	v_pk_mul_f32 v[44:45], v[0:1], v[44:45] op_sel_hi:[0,1]
	v_mul_f32_e32 v1, 0xbfb8aa3b, v34
	v_pk_mul_f32 v[40:41], v[40:41], v[42:43]
	v_exp_f32_e32 v1, v1
	v_mul_f32_e32 v42, 0xbfb8aa3b, v35
	v_exp_f32_e32 v43, v42
	v_pk_mul_f32 v[44:45], v[120:121], v[44:45]
	v_add_f32_e32 v1, 1.0, v1
	v_rcp_f32_e32 v42, v1
	v_add_f32_e32 v1, 1.0, v43
	v_rcp_f32_e32 v43, v1
	v_pk_mul_f32 v[40:41], v[40:41], v[44:45]
	v_lshlrev_b32_e32 v44, 16, v164
	v_and_b32_e32 v45, 0xffff0000, v164
	v_pk_mul_f32 v[44:45], v[0:1], v[44:45] op_sel_hi:[0,1]
	v_mul_f32_e32 v1, 0xbfb8aa3b, v36
	v_pk_mul_f32 v[34:35], v[34:35], v[42:43]
	v_exp_f32_e32 v1, v1
	v_mul_f32_e32 v42, 0xbfb8aa3b, v37
	v_exp_f32_e32 v48, v42
	v_pk_mul_f32 v[44:45], v[114:115], v[44:45]
	v_add_f32_e32 v1, 1.0, v1
	v_pk_mul_f32 v[42:43], v[34:35], v[44:45]
	v_rcp_f32_e32 v34, v1
	v_add_f32_e32 v1, 1.0, v48
	v_rcp_f32_e32 v35, v1
	v_lshlrev_b32_e32 v44, 16, v165
	v_and_b32_e32 v45, 0xffff0000, v165
	v_pk_mul_f32 v[0:1], v[0:1], v[44:45] op_sel_hi:[0,1]
	v_pk_mul_f32 v[0:1], v[116:117], v[0:1]
	v_pk_mul_f32 v[34:35], v[36:37], v[34:35]
	v_cvt_pk_bf16_f32 v36, v42, v43
	v_pk_mul_f32 v[0:1], v[34:35], v[0:1]
	v_cvt_pk_bf16_f32 v34, v38, v39
	v_cvt_pk_bf16_f32 v35, v40, v41
	v_cvt_pk_bf16_f32 v37, v0, v1
	v_mul_f32_e32 v0, 0xbfb8aa3b, v30
	global_store_dwordx4 v[46:47], v[34:37], off offset:256
	s_nop 1
	v_exp_f32_e32 v34, v0
	v_mul_f32_e32 v0, 0xbfb8aa3b, v31
	v_exp_f32_e32 v35, v0
	ds_read2_b32 v[0:1], v222 offset0:160 offset1:176
	v_add_f32_e32 v34, 1.0, v34
	v_rcp_f32_e32 v34, v34
	v_add_f32_e32 v35, 1.0, v35
	v_rcp_f32_e32 v35, v35
	v_lshlrev_b32_e32 v36, 16, v150
	v_and_b32_e32 v37, 0xffff0000, v150
	s_waitcnt lgkmcnt(0)
	v_pk_mul_f32 v[36:37], v[0:1], v[36:37] op_sel_hi:[0,1]
	v_pk_mul_f32 v[30:31], v[30:31], v[34:35]
	v_mul_f32_e32 v34, 0xbfb8aa3b, v32
	v_mul_f32_e32 v35, 0xbfb8aa3b, v33
	v_exp_f32_e32 v34, v34
	v_exp_f32_e32 v35, v35
	v_pk_mul_f32 v[36:37], v[106:107], v[36:37]
	v_add_f32_e32 v34, 1.0, v34
	v_add_f32_e32 v35, 1.0, v35
	v_rcp_f32_e32 v34, v34
	v_rcp_f32_e32 v35, v35
	v_pk_mul_f32 v[30:31], v[30:31], v[36:37]
	v_lshlrev_b32_e32 v36, 16, v151
	v_and_b32_e32 v37, 0xffff0000, v151
	v_pk_mul_f32 v[32:33], v[32:33], v[34:35]
	v_mul_f32_e32 v34, 0xbfb8aa3b, v26
	v_mul_f32_e32 v35, 0xbfb8aa3b, v27
	v_exp_f32_e32 v34, v34
	v_exp_f32_e32 v35, v35
	v_pk_mul_f32 v[36:37], v[0:1], v[36:37] op_sel_hi:[0,1]
	v_pk_mul_f32 v[36:37], v[108:109], v[36:37]
	v_add_f32_e32 v34, 1.0, v34
	v_add_f32_e32 v35, 1.0, v35
	v_rcp_f32_e32 v34, v34
	v_rcp_f32_e32 v35, v35
	v_pk_mul_f32 v[32:33], v[32:33], v[36:37]
	v_lshlrev_b32_e32 v36, 16, v152
	v_and_b32_e32 v37, 0xffff0000, v152
	v_pk_mul_f32 v[26:27], v[26:27], v[34:35]
	v_mul_f32_e32 v34, 0xbfb8aa3b, v28
	v_exp_f32_e32 v38, v34
	v_mul_f32_e32 v34, 0xbfb8aa3b, v29
	v_exp_f32_e32 v39, v34
	v_pk_mul_f32 v[36:37], v[0:1], v[36:37] op_sel_hi:[0,1]
	v_pk_mul_f32 v[36:37], v[98:99], v[36:37]
	s_nop 0
	v_pk_mul_f32 v[34:35], v[26:27], v[36:37]
	v_add_f32_e32 v26, 1.0, v38
	v_add_f32_e32 v27, 1.0, v39
	v_rcp_f32_e32 v26, v26
	v_rcp_f32_e32 v27, v27
	v_lshlrev_b32_e32 v36, 16, v153
	v_and_b32_e32 v37, 0xffff0000, v153
	v_pk_mul_f32 v[36:37], v[0:1], v[36:37] op_sel_hi:[0,1]
	v_pk_mul_f32 v[36:37], v[100:101], v[36:37]
	v_pk_mul_f32 v[26:27], v[28:29], v[26:27]
	v_cvt_pk_bf16_f32 v28, v34, v35
	v_pk_mul_f32 v[36:37], v[26:27], v[36:37]
	v_cvt_pk_bf16_f32 v27, v32, v33
	v_mul_f32_e32 v32, 0xbfb8aa3b, v22
	v_mul_f32_e32 v33, 0xbfb8aa3b, v23
	v_exp_f32_e32 v32, v32
	v_exp_f32_e32 v33, v33
	v_cvt_pk_bf16_f32 v26, v30, v31
	v_lshl_add_u64 v[30:31], s[4:5], 0, v[206:207]
	v_cvt_pk_bf16_f32 v29, v36, v37
	v_lshl_add_u64 v[30:31], v[30:31], 0, v[202:203]
	global_store_dwordx4 v[30:31], v[26:29], off
	s_nop 1
	v_add_f32_e32 v26, 1.0, v32
	v_add_f32_e32 v27, 1.0, v33
	v_rcp_f32_e32 v26, v26
	v_rcp_f32_e32 v27, v27
	v_lshlrev_b32_e32 v28, 16, v142
	v_and_b32_e32 v29, 0xffff0000, v142
	v_pk_mul_f32 v[28:29], v[0:1], v[28:29] op_sel_hi:[0,1]
	v_pk_mul_f32 v[22:23], v[22:23], v[26:27]
	v_mul_f32_e32 v26, 0xbfb8aa3b, v24
	v_mul_f32_e32 v27, 0xbfb8aa3b, v25
	v_exp_f32_e32 v26, v26
	v_exp_f32_e32 v27, v27
	v_pk_mul_f32 v[28:29], v[118:119], v[28:29]
	v_add_f32_e32 v26, 1.0, v26
	v_add_f32_e32 v27, 1.0, v27
	v_rcp_f32_e32 v26, v26
	v_rcp_f32_e32 v27, v27
	v_pk_mul_f32 v[22:23], v[22:23], v[28:29]
	v_lshlrev_b32_e32 v28, 16, v143
	v_and_b32_e32 v29, 0xffff0000, v143
	v_pk_mul_f32 v[24:25], v[24:25], v[26:27]
	v_mul_f32_e32 v26, 0xbfb8aa3b, v18
	v_mul_f32_e32 v27, 0xbfb8aa3b, v19
	v_exp_f32_e32 v26, v26
	v_exp_f32_e32 v27, v27
	v_pk_mul_f32 v[28:29], v[0:1], v[28:29] op_sel_hi:[0,1]
	v_pk_mul_f32 v[28:29], v[120:121], v[28:29]
	v_add_f32_e32 v26, 1.0, v26
	v_add_f32_e32 v27, 1.0, v27
	v_rcp_f32_e32 v26, v26
	v_rcp_f32_e32 v27, v27
	v_pk_mul_f32 v[24:25], v[24:25], v[28:29]
	v_lshlrev_b32_e32 v28, 16, v144
	v_and_b32_e32 v29, 0xffff0000, v144
	v_pk_mul_f32 v[18:19], v[18:19], v[26:27]
	v_mul_f32_e32 v26, 0xbfb8aa3b, v20
	v_exp_f32_e32 v32, v26
	v_mul_f32_e32 v26, 0xbfb8aa3b, v21
	v_exp_f32_e32 v33, v26
	v_pk_mul_f32 v[28:29], v[0:1], v[28:29] op_sel_hi:[0,1]
	v_pk_mul_f32 v[28:29], v[114:115], v[28:29]
	s_nop 0
	v_pk_mul_f32 v[26:27], v[18:19], v[28:29]
	v_add_f32_e32 v18, 1.0, v32
	v_add_f32_e32 v19, 1.0, v33
	v_rcp_f32_e32 v18, v18
	v_rcp_f32_e32 v19, v19
	v_lshlrev_b32_e32 v28, 16, v145
	v_and_b32_e32 v29, 0xffff0000, v145
	v_pk_mul_f32 v[28:29], v[0:1], v[28:29] op_sel_hi:[0,1]
	v_pk_mul_f32 v[28:29], v[116:117], v[28:29]
	v_pk_mul_f32 v[18:19], v[20:21], v[18:19]
	v_mul_f32_e32 v0, 0xbfb8aa3b, v14
	v_pk_mul_f32 v[28:29], v[18:19], v[28:29]
	v_cvt_pk_bf16_f32 v18, v22, v23
	v_exp_f32_e32 v0, v0
	v_mul_f32_e32 v22, 0xbfb8aa3b, v15
	v_exp_f32_e32 v22, v22
	v_cvt_pk_bf16_f32 v19, v24, v25
	v_cvt_pk_bf16_f32 v20, v26, v27
	v_cvt_pk_bf16_f32 v21, v28, v29
	v_add_f32_e32 v0, 1.0, v0
	global_store_dwordx4 v[30:31], v[18:21], off offset:256
	s_nop 1
	v_rcp_f32_e32 v18, v0
	v_add_f32_e32 v0, 1.0, v22
	v_rcp_f32_e32 v19, v0
	v_lshlrev_b32_e32 v20, 16, v126
	v_and_b32_e32 v21, 0xffff0000, v126
	v_mov_b32_e32 v0, v1
	v_pk_mul_f32 v[20:21], v[0:1], v[20:21] op_sel_hi:[0,1]
	v_mul_f32_e32 v1, 0xbfb8aa3b, v16
	v_pk_mul_f32 v[14:15], v[14:15], v[18:19]
	v_exp_f32_e32 v1, v1
	v_mul_f32_e32 v18, 0xbfb8aa3b, v17
	v_exp_f32_e32 v19, v18
	v_pk_mul_f32 v[20:21], v[106:107], v[20:21]
	v_add_f32_e32 v1, 1.0, v1
	v_rcp_f32_e32 v18, v1
	v_add_f32_e32 v1, 1.0, v19
	v_rcp_f32_e32 v19, v1
	v_pk_mul_f32 v[14:15], v[14:15], v[20:21]
	v_lshlrev_b32_e32 v20, 16, v127
	v_and_b32_e32 v21, 0xffff0000, v127
	v_pk_mul_f32 v[20:21], v[0:1], v[20:21] op_sel_hi:[0,1]
	v_mul_f32_e32 v1, 0xbfb8aa3b, v10
	v_pk_mul_f32 v[16:17], v[16:17], v[18:19]
	v_exp_f32_e32 v1, v1
	v_mul_f32_e32 v18, 0xbfb8aa3b, v11
	v_exp_f32_e32 v19, v18
	v_pk_mul_f32 v[20:21], v[108:109], v[20:21]
	v_add_f32_e32 v1, 1.0, v1
	v_rcp_f32_e32 v18, v1
	v_add_f32_e32 v1, 1.0, v19
	v_rcp_f32_e32 v19, v1
	v_pk_mul_f32 v[16:17], v[16:17], v[20:21]
	v_lshlrev_b32_e32 v20, 16, v128
	v_and_b32_e32 v21, 0xffff0000, v128
	v_pk_mul_f32 v[20:21], v[0:1], v[20:21] op_sel_hi:[0,1]
	v_mul_f32_e32 v1, 0xbfb8aa3b, v12
	v_pk_mul_f32 v[10:11], v[10:11], v[18:19]
	v_exp_f32_e32 v1, v1
	v_mul_f32_e32 v18, 0xbfb8aa3b, v13
	v_exp_f32_e32 v22, v18
	v_pk_mul_f32 v[20:21], v[98:99], v[20:21]
	v_add_f32_e32 v1, 1.0, v1
; DEV int opaque_tid() { int t = threadIdx.x; asm volatile("" : "+v"(t)); return t; }
; #define G8_STAGE(bufoff, gbase, voff) do { _Pragma("unroll") for (int _i = 0; _i < 2; ++_i) \
;         __builtin_amdgcn_global_load_lds((const unsigned*)((const char*)(gbase) + (voff)[_i]), (LAS unsigned*)(lds + (bufoff) + ldsw + _i * 8192), 16, 0, 0); } while (0)
; #define G8_BAR __builtin_amdgcn_s_barrier()
; template <class Epi, class Sched>
; DEV void gemm_phase(LAS char* lds, const Sched& S, const Epi& E) {
;     const int tid = opaque_tid(), wid = __builtin_amdgcn_readfirstlane(tid >> 6), lane = tid & 63, wr = wid >> 2, wc = wid & 3, fr = lane & 15, fq = lane >> 4;
;     constexpr int lda = Sched::lda, ldb = Sched::ldb, nt = Sched::K / BK;
;     unsigned voffA[2], voffB[2];
; #pragma unroll
;     for (int i = 0; i < 2; ++i) { int R, C; stage_rc(tid * 16 + i * 8192, R, C); const int Rb = (R & ~31) + perm32(R & 31);
;         voffA[i] = Sched::aoff(R, C); voffB[i] = (unsigned)(Rb * ldb + C) * 2u; asm volatile("" : "+v"(voffA[i]), "+v"(voffB[i])); }
;     constexpr size_t kstep = (size_t)(BK * 2), kstepA = Sched::kstepA, hstepA = Sched::hstepA, hstepB = Sched::hstepB;
;     const unsigned ldsw = (unsigned)wid * 1024u;
;     const int aoff = lds_byte(wr * 64 + fr, fq * 8), boff = lds_byte(wc * 32 + fr, fq * 8);
;     ...
;     Unit cur, nxt; int ui = 0;
;     __syncthreads();
;     if (!S.next(0, cur)) return;
;     f32x4 acc[2][2][4][2];
; #pragma unroll
;     for (int a = 0; a < 2; ++a)
; #pragma unroll
;         for (int b = 0; b < 2; ++b)
; #pragma unroll
;             for (int m = 0; m < 4; ++m)
; #pragma unroll
;                 for (int n = 0; n < 2; ++n) acc[a][b][m][n] = (f32x4){0.f, 0.f, 0.f, 0.f};
;     bf16x8 At[4][2], B0[2][2], B1[2][2];
;     const char* cA = cur.A; const char* cA2 = cur.A2; const char* cB = cur.B;
;     constexpr int KSP = Sched::ksplit;
;     ...
;     G8_STAGE(G8_SB(0, 0), cB, voffB); G8_STAGE(G8_SB(0, 1), cB + hstepB, voffB); G8_STAGE(G8_SA(0, 0), cA, voffA); G8_STAGE(G8_SA(0, 1), cA + hstepA, voffA);
;     if (wr == 1) G8_BAR;
	v_pk_mul_f32 v[18:19], v[10:11], v[20:21]
	v_rcp_f32_e32 v10, v1
	v_add_f32_e32 v1, 1.0, v22
	v_rcp_f32_e32 v11, v1
	v_lshlrev_b32_e32 v20, 16, v129
	v_and_b32_e32 v21, 0xffff0000, v129
	v_pk_mul_f32 v[20:21], v[0:1], v[20:21] op_sel_hi:[0,1]
	v_pk_mul_f32 v[20:21], v[100:101], v[20:21]
	v_pk_mul_f32 v[10:11], v[12:13], v[10:11]
	v_mul_f32_e32 v1, 0xbfb8aa3b, v6
	v_pk_mul_f32 v[20:21], v[10:11], v[20:21]
	v_cvt_pk_bf16_f32 v11, v16, v17
	v_exp_f32_e32 v1, v1
	v_mul_f32_e32 v16, 0xbfb8aa3b, v7
	v_exp_f32_e32 v16, v16
	v_cvt_pk_bf16_f32 v10, v14, v15
	v_lshl_add_u64 v[14:15], s[4:5], 0, v[204:205]
	v_cvt_pk_bf16_f32 v12, v18, v19
	v_cvt_pk_bf16_f32 v13, v20, v21
	v_lshl_add_u64 v[14:15], v[14:15], 0, v[202:203]
	v_add_f32_e32 v1, 1.0, v1
	global_store_dwordx4 v[14:15], v[10:13], off
	s_nop 1
	v_rcp_f32_e32 v10, v1
	v_add_f32_e32 v1, 1.0, v16
	v_rcp_f32_e32 v11, v1
	v_lshlrev_b32_e32 v12, 16, v110
	v_and_b32_e32 v13, 0xffff0000, v110
	v_pk_mul_f32 v[12:13], v[0:1], v[12:13] op_sel_hi:[0,1]
	v_mul_f32_e32 v1, 0xbfb8aa3b, v8
	v_pk_mul_f32 v[6:7], v[6:7], v[10:11]
	v_exp_f32_e32 v1, v1
	v_mul_f32_e32 v10, 0xbfb8aa3b, v9
	v_exp_f32_e32 v11, v10
	v_pk_mul_f32 v[12:13], v[118:119], v[12:13]
	v_add_f32_e32 v1, 1.0, v1
	v_rcp_f32_e32 v10, v1
	v_add_f32_e32 v1, 1.0, v11
	v_rcp_f32_e32 v11, v1
	v_pk_mul_f32 v[6:7], v[6:7], v[12:13]
	v_lshlrev_b32_e32 v12, 16, v111
	v_and_b32_e32 v13, 0xffff0000, v111
	v_pk_mul_f32 v[12:13], v[0:1], v[12:13] op_sel_hi:[0,1]
	v_mul_f32_e32 v1, 0xbfb8aa3b, v2
	v_pk_mul_f32 v[8:9], v[8:9], v[10:11]
	v_exp_f32_e32 v1, v1
	v_mul_f32_e32 v10, 0xbfb8aa3b, v3
	v_exp_f32_e32 v11, v10
	v_pk_mul_f32 v[12:13], v[120:121], v[12:13]
	v_add_f32_e32 v1, 1.0, v1
	v_rcp_f32_e32 v10, v1
	v_add_f32_e32 v1, 1.0, v11
	v_rcp_f32_e32 v11, v1
	v_pk_mul_f32 v[8:9], v[8:9], v[12:13]
	v_lshlrev_b32_e32 v12, 16, v112
	v_and_b32_e32 v13, 0xffff0000, v112
	v_pk_mul_f32 v[12:13], v[0:1], v[12:13] op_sel_hi:[0,1]
	v_mul_f32_e32 v1, 0xbfb8aa3b, v4
	v_pk_mul_f32 v[2:3], v[2:3], v[10:11]
	v_exp_f32_e32 v1, v1
	v_mul_f32_e32 v10, 0xbfb8aa3b, v5
	v_exp_f32_e32 v16, v10
	v_pk_mul_f32 v[12:13], v[114:115], v[12:13]
	v_add_f32_e32 v1, 1.0, v1
	v_pk_mul_f32 v[10:11], v[2:3], v[12:13]
	v_rcp_f32_e32 v2, v1
	v_add_f32_e32 v1, 1.0, v16
	v_rcp_f32_e32 v3, v1
	v_lshlrev_b32_e32 v12, 16, v113
	v_and_b32_e32 v13, 0xffff0000, v113
	v_pk_mul_f32 v[0:1], v[0:1], v[12:13] op_sel_hi:[0,1]
	v_pk_mul_f32 v[0:1], v[116:117], v[0:1]
	v_pk_mul_f32 v[2:3], v[4:5], v[2:3]
	v_cvt_pk_bf16_f32 v4, v10, v11
	v_pk_mul_f32 v[0:1], v[2:3], v[0:1]
	v_cvt_pk_bf16_f32 v2, v6, v7
	v_cvt_pk_bf16_f32 v3, v8, v9
	v_cvt_pk_bf16_f32 v5, v0, v1
	v_mov_b32_e32 v0, s0
	s_add_i32 s0, 0, 0x24ef4
	global_store_dwordx4 v[14:15], v[2:5], off offset:256
	s_waitcnt vmcnt(0)
	s_barrier
	ds_read_b32 v1, v0
	v_mov_b32_e32 v2, s0
	ds_read_b32 v3, v2
	v_mov_b32_e32 v10, v254
	s_waitcnt lgkmcnt(1)
	v_readfirstlane_b32 s2, v1
	s_waitcnt lgkmcnt(0)
	v_readfirstlane_b32 s4, v3
	ds_read_b32 v1, v0
	ds_read_b32 v3, v2
	ds_read_b32 v4, v0
	ds_read_b32 v5, v2
	ds_read_b32 v6, v0
	s_waitcnt lgkmcnt(4)
	v_readfirstlane_b32 s5, v1
	s_waitcnt lgkmcnt(3)
	v_readfirstlane_b32 s9, v3
	s_waitcnt lgkmcnt(2)
	v_readfirstlane_b32 s10, v4
	ds_read_b32 v1, v2
	ds_read_b32 v3, v0
	ds_read_b32 v4, v2
	ds_read_b32 v0, v0
	ds_read_b32 v2, v2
	s_waitcnt lgkmcnt(6)
	v_readfirstlane_b32 s11, v5
	s_waitcnt lgkmcnt(2)
	v_readfirstlane_b32 s6, v4
	s_waitcnt lgkmcnt(1)
	v_readfirstlane_b32 s7, v0
	v_lshlrev_b32_e32 v0, 4, v10
	s_waitcnt lgkmcnt(0)
	v_readfirstlane_b32 s8, v2
	v_bfe_u32 v2, v0, 6, 4
	v_ashrrev_i32_e32 v4, 3, v10
	v_readfirstlane_b32 s12, v6
	v_and_or_b32 v5, v4, s14, v2
	v_and_b32_e32 v6, 0x7fffe0, v4
	v_lshrrev_b32_e32 v4, 2, v4
	v_readfirstlane_b32 s13, v1
	v_and_b32_e32 v1, 32, v10
	v_and_or_b32 v4, v4, 4, v6
	v_lshrrev_b32_e32 v6, 1, v10
	v_readfirstlane_b32 s1, v3
	v_bitop3_b32 v1, v0, v1, 48 bitop3:0x6c
	v_bfe_u32 v3, v0, 6, 2
	v_and_b32_e32 v6, 24, v6
	v_add_u32_e32 v0, 0x2000, v0
	v_and_or_b32 v1, v10, 64, v1
	v_or3_b32 v4, v4, v6, v3
	v_ashrrev_i32_e32 v0, 7, v0
	v_lshl_or_b32 v132, v4, 9, v1
	v_lshrrev_b32_e32 v4, 2, v0
	v_and_b32_e32 v4, 4, v4
	v_and_or_b32 v2, v0, s14, v2
	v_and_or_b32 v0, v0, s15, v4
	v_readlane_b32 s14, v255, 25
	v_or3_b32 v0, v0, v6, v3
	v_readlane_b32 s15, v255, 26
	v_readfirstlane_b32 s0, v10
	v_lshl_or_b32 v130, v5, 11, v1
	v_lshl_or_b32 v134, v2, 11, v1
	v_lshl_or_b32 v136, v0, 9, v1
	s_and_b64 vcc, exec, s[14:15]
	s_barrier
	s_cbranch_vccz .LBB0_1384
	s_add_u32 s2, s2, 0x8048000
	s_addc_u32 s44, s4, 0
	s_add_u32 s45, s5, 0xa05a000
	s_addc_u32 s46, s9, 0
	v_readlane_b32 s14, v255, 23
	s_add_u32 s47, s10, 0xec7e000
	v_readlane_b32 s15, v255, 24
	s_addc_u32 s53, s11, 0
	s_ashr_i32 s10, s0, 6
	s_ashr_i32 s65, s64, 31
	s_ashr_i32 s15, s14, 31
	s_ashr_i32 s9, s0, 8
	s_lshl_b32 s54, s10, 10
	s_lshl_b64 s[4:5], s[64:65], 17
	s_mov_b32 s80, s14
	s_lshl_b64 s[14:15], s[14:15], 19
	s_and_b32 s11, s64, -4
	s_cmp_eq_u32 s11, 8
	s_cselect_b32 s16, s45, s2
	s_cselect_b32 s11, s46, s44
	s_add_u32 s14, s16, s14
	s_addc_u32 s11, s11, s15
	s_lshl_b32 s15, s64, 9
	s_and_b32 s15, s15, 0x600
	s_add_u32 s24, s14, s15
	s_addc_u32 s25, s11, 0
	s_add_u32 s26, s47, s4
	s_addc_u32 s27, s53, s5
	s_add_i32 s55, s54, 0
	s_add_i32 m0, s55, 0x10000
	v_mov_b32_e32 v139, 0
	global_load_lds_dwordx4 v132, s[26:27]
	s_add_i32 m0, s55, 0x12000
	s_add_u32 s4, s26, 0x10000
	global_load_lds_dwordx4 v136, s[26:27]
	s_addc_u32 s5, s27, 0
	s_add_i32 m0, s55, 0x14000
	s_add_i32 s56, s55, 0x2000
	global_load_lds_dwordx4 v132, s[4:5]
	s_add_i32 m0, s55, 0x16000
	v_mov_b32_e32 v133, v139
	global_load_lds_dwordx4 v136, s[4:5]
	s_mov_b32 m0, s55
	s_add_u32 s4, s24, 0x40000
	global_load_lds_dwordx4 v130, s[24:25]
	s_mov_b32 m0, s56
	s_addc_u32 s5, s25, 0
	s_add_i32 s57, s55, 0x4000
	global_load_lds_dwordx4 v134, s[24:25]
	s_mov_b32 m0, s57
	s_add_i32 s59, s55, 0x6000
	global_load_lds_dwordx4 v130, s[4:5]
	s_mov_b32 m0, s59
	v_mov_b32_e32 v137, v139
	global_load_lds_dwordx4 v134, s[4:5]
	v_mov_b32_e32 v131, v139
	v_mov_b32_e32 v135, v139
	s_cmp_eq_u32 s9, 1
	v_lshl_add_u64 v[8:9], s[26:27], 0, v[132:133]
	v_lshl_add_u64 v[6:7], s[26:27], 0, v[136:137]
	v_lshl_add_u64 v[2:3], s[24:25], 0, v[130:131]
	s_cselect_b64 s[4:5], -1, 0
	s_cmp_lg_u32 s9, 1
	v_lshl_add_u64 v[4:5], s[24:25], 0, v[134:135]
	s_cbranch_scc1 .LBB0_1367
	s_barrier

; __global__ void __launch_bounds__(512, 2) mega(Params Pk) {
	.amdhsa_kernel _Z4mega6Params
		.amdhsa_group_segment_fixed_size 0
		.amdhsa_private_segment_fixed_size 0
		.amdhsa_kernarg_size 504
		.amdhsa_user_sgpr_count 2
		.amdhsa_user_sgpr_dispatch_ptr 0
		.amdhsa_user_sgpr_queue_ptr 0
		.amdhsa_user_sgpr_kernarg_segment_ptr 1
		.amdhsa_user_sgpr_dispatch_id 0
		.amdhsa_user_sgpr_kernarg_preload_length 0
		.amdhsa_user_sgpr_kernarg_preload_offset 0
		.amdhsa_user_sgpr_private_segment_size 0
		.amdhsa_uses_dynamic_stack 0
		.amdhsa_enable_private_segment 0
		.amdhsa_system_sgpr_workgroup_id_x 1
		.amdhsa_system_sgpr_workgroup_id_y 0
		.amdhsa_system_sgpr_workgroup_id_z 0
		.amdhsa_system_sgpr_workgroup_info 0
		.amdhsa_system_vgpr_workitem_id 0
		.amdhsa_next_free_vgpr 256
		.amdhsa_next_free_sgpr 102
		.amdhsa_accum_offset 256
		.amdhsa_reserve_vcc 1
		.amdhsa_float_round_mode_32 0
		.amdhsa_float_round_mode_16_64 0
		.amdhsa_float_denorm_mode_32 3
		.amdhsa_float_denorm_mode_16_64 3
		.amdhsa_dx10_clamp 1
		.amdhsa_ieee_mode 1
		.amdhsa_fp16_overflow 0
		.amdhsa_tg_split 0
		.amdhsa_exception_fp_ieee_invalid_op 0
		.amdhsa_exception_fp_denorm_src 0
		.amdhsa_exception_fp_ieee_div_zero 0
		.amdhsa_exception_fp_ieee_overflow 0
		.amdhsa_exception_fp_ieee_underflow 0
		.amdhsa_exception_fp_ieee_inexact 0
		.amdhsa_exception_int_div_zero 0
	.end_amdhsa_kernel

; __global__ void __launch_bounds__(512, 2) mega(Params Pk) {
amdhsa.kernels:
  - .agpr_count:     0
    .args:
      - .offset:         0
        .size:           248
        .value_kind:     by_value
      - .offset:         248
        .size:           4
        .value_kind:     hidden_block_count_x
      - .offset:         252
        .size:           4
        .value_kind:     hidden_block_count_y
      - .offset:         256
        .size:           4
        .value_kind:     hidden_block_count_z
      - .offset:         260
        .size:           2
        .value_kind:     hidden_group_size_x
      - .offset:         262
        .size:           2
        .value_kind:     hidden_group_size_y
      - .offset:         264
        .size:           2
        .value_kind:     hidden_group_size_z
      - .offset:         266
        .size:           2
        .value_kind:     hidden_remainder_x
      - .offset:         268
        .size:           2
        .value_kind:     hidden_remainder_y
      - .offset:         270
        .size:           2
        .value_kind:     hidden_remainder_z
      - .offset:         288
        .size:           8
        .value_kind:     hidden_global_offset_x
      - .offset:         296
        .size:           8
        .value_kind:     hidden_global_offset_y
      - .offset:         304
        .size:           8
        .value_kind:     hidden_global_offset_z
      - .offset:         312
        .size:           2
        .value_kind:     hidden_grid_dims
      - .offset:         368
        .size:           4
        .value_kind:     hidden_dynamic_lds_size
    .group_segment_fixed_size: 0
    .kernarg_segment_align: 8
    .kernarg_segment_size: 504
    .language:       OpenCL C
    .language_version:
      - 2
      - 0
    .max_flat_workgroup_size: 512
    .name:           _Z4mega6Params
    .private_segment_fixed_size: 0
    .sgpr_count:     108
    .sgpr_spill_count: 63
    .symbol:         _Z4mega6Params.kd
    .uniform_work_group_size: 1
    .uses_dynamic_stack: false
    .vgpr_count:     256
    .vgpr_spill_count: 0
    .wavefront_size: 64
